# v17
# speedup vs baseline: 1.0092x; 1.0092x over previous
; #define PG8_STAGE(bufoff, gbase, voff) do { const __amdgpu_buffer_rsrc_t _rs = __builtin_amdgcn_make_buffer_rsrc((void*)(gbase), 0, 0x7fffffff, 0x00020000); _Pragma("unroll") for (int _i = 0; _i < 2; ++_i) \
;         __builtin_amdgcn_raw_ptr_buffer_load_lds(_rs, (LAS unsigned*)(lds + (bufoff) + ldsw + _i * 8192), 16, (int)(voff)[_i], 0, 0, 0); } while (0)
; #define PG8_WAIT_V(n) asm volatile("s_waitcnt vmcnt(" #n ")" ::: "memory")
; #define PG8_WAIT_L(n) asm volatile("s_waitcnt lgkmcnt(" #n ")" ::: "memory")
; #define PG8_BAR __builtin_amdgcn_s_barrier()
; #define PG8_SCHED __builtin_amdgcn_sched_barrier(0)
; template <class Epi, class Sched, bool F8 = false>
; __device__ __forceinline__ void gemm_phase(LAS unsigned char* lds, const int lda, const int ldb, const Sched& S, const Epi& E) {
;     ...
;             const bool last = (t == nt - 2);
;             const char* a1 = cA + (size_t)(t + 1) * kstep;
;             const char* a2 = last ? nA : cA + (size_t)(t + 2) * kstep; const char* b2 = last ? nB : cB + (size_t)(t + 2) * kstepB;
;             const char* a3 = a2 + kstep; const char* b3 = b2 + kstepB;
;     ...
;             PG8_LDB(B0, 0, 0); PG8_LDB(B1, 0, 1); PG8_SCHED; PG8_LDA(At, 0, 0); PG8_STAGE(PG8_SA(1, 1), a1 + hstepA, voffA);
;             PG8_WAIT_V(8); PG8_WAIT_L(0); PG8_BAR; PG8_MMA(0, 0, At, B0); PG8_MMA(0, 1, At, B1); PG8_BAR; PG8_SCHED;
;             PG8_LDA(At, 0, 1); PG8_STAGE(PG8_SB(0, 0), b2, voffB); PG8_STAGE(PG8_SB(0, 1), b2 + hstepB, voffB); PG8_STAGE(PG8_SA(0, 0), a2, voffA);
;             PG8_WAIT_V(8); PG8_WAIT_L(0); PG8_BAR; PG8_MMA(1, 0, At, B0); PG8_MMA(1, 1, At, B1); PG8_BAR; PG8_SCHED;
.LBB0_116:
	ds_read_b128 v[132:135], v140
	ds_read_b128 v[146:149], v140 offset:1024
	ds_read_b128 v[150:153], v140 offset:2048
	ds_read_b128 v[154:157], v140 offset:3072
	ds_read_b128 v[158:161], v141
	ds_read_b128 v[162:165], v141 offset:1024
	ds_read_b128 v[166:169], v141 offset:2048
	ds_read_b128 v[174:177], v141 offset:3072
	s_add_u32 s16, s63, 0xfff00080
	s_addc_u32 s17, s67, -1
	s_cmp_eq_u32 s69, 60
	s_cselect_b32 s28, s70, s16
	s_cselect_b32 s23, s71, s17
	s_cselect_b32 s22, s73, s62
	s_cselect_b32 s24, s72, s7
	s_add_u32 s20, s28, 0x80
	s_addc_u32 s21, s23, 0
	s_and_b32 s17, s67, 0xffff
	s_mov_b32 s16, s63
	s_mov_b32 m0, s93
	ds_read_b128 v[178:181], v142
	ds_read_b128 v[182:185], v142 offset:1024
	ds_read_b128 v[186:189], v142 offset:2048
	ds_read_b128 v[190:193], v142 offset:3072
	ds_read_b128 v[194:197], v142 offset:4096
	ds_read_b128 v[198:201], v142 offset:5120
	ds_read_b128 v[202:205], v142 offset:6144
	ds_read_b128 v[206:209], v142 offset:7168
	buffer_load_dwordx4 v136, s[16:19], 0 offen lds
	s_mov_b32 m0, s94
	s_nop 0
	buffer_load_dwordx4 v138, s[16:19], 0 offen lds
	s_waitcnt vmcnt(8)
	s_waitcnt lgkmcnt(0)
	s_barrier
	s_setprio 1
	v_mfma_f32_16x16x32_bf16 v[124:127], v[132:135], v[178:181], v[124:127]
	v_mfma_f32_16x16x32_bf16 v[120:123], v[150:153], v[178:181], v[120:123]
	v_mfma_f32_16x16x32_bf16 v[108:111], v[132:135], v[186:189], v[108:111]
	v_mfma_f32_16x16x32_bf16 v[104:107], v[150:153], v[186:189], v[104:107]
	v_mfma_f32_16x16x32_bf16 v[92:95], v[132:135], v[194:197], v[92:95]
	v_mfma_f32_16x16x32_bf16 v[88:91], v[150:153], v[194:197], v[88:91]
	v_mfma_f32_16x16x32_bf16 v[76:79], v[132:135], v[202:205], v[76:79]
	v_mfma_f32_16x16x32_bf16 v[72:75], v[150:153], v[202:205], v[72:75]
	v_mfma_f32_16x16x32_bf16 v[124:127], v[146:149], v[182:185], v[124:127]
	v_mfma_f32_16x16x32_bf16 v[120:123], v[154:157], v[182:185], v[120:123]
	v_mfma_f32_16x16x32_bf16 v[108:111], v[146:149], v[190:193], v[108:111]
	v_mfma_f32_16x16x32_bf16 v[104:107], v[154:157], v[190:193], v[104:107]
	v_mfma_f32_16x16x32_bf16 v[92:95], v[146:149], v[198:201], v[92:95]
	v_mfma_f32_16x16x32_bf16 v[88:91], v[154:157], v[198:201], v[88:91]
	v_mfma_f32_16x16x32_bf16 v[76:79], v[146:149], v[206:209], v[76:79]
	v_mfma_f32_16x16x32_bf16 v[72:75], v[154:157], v[206:209], v[72:75]
	s_setprio 0
	s_setprio 1
	v_mfma_f32_16x16x32_bf16 v[116:119], v[158:161], v[178:181], v[116:119]
	v_mfma_f32_16x16x32_bf16 v[112:115], v[166:169], v[178:181], v[112:115]
	v_mfma_f32_16x16x32_bf16 v[100:103], v[158:161], v[186:189], v[100:103]
	v_mfma_f32_16x16x32_bf16 v[96:99], v[166:169], v[186:189], v[96:99]
	v_mfma_f32_16x16x32_bf16 v[84:87], v[158:161], v[194:197], v[84:87]
	v_mfma_f32_16x16x32_bf16 v[80:83], v[166:169], v[194:197], v[80:83]
	v_mfma_f32_16x16x32_bf16 v[68:71], v[158:161], v[202:205], v[68:71]
	v_mfma_f32_16x16x32_bf16 v[64:67], v[166:169], v[202:205], v[64:67]
	v_mfma_f32_16x16x32_bf16 v[116:119], v[162:165], v[182:185], v[116:119]
	v_mfma_f32_16x16x32_bf16 v[112:115], v[174:177], v[182:185], v[112:115]
	v_mfma_f32_16x16x32_bf16 v[100:103], v[162:165], v[190:193], v[100:103]
	v_mfma_f32_16x16x32_bf16 v[96:99], v[174:177], v[190:193], v[96:99]
	v_mfma_f32_16x16x32_bf16 v[84:87], v[162:165], v[198:201], v[84:87]
	v_mfma_f32_16x16x32_bf16 v[80:83], v[174:177], v[198:201], v[80:83]
	v_mfma_f32_16x16x32_bf16 v[68:71], v[162:165], v[206:209], v[68:71]
	v_mfma_f32_16x16x32_bf16 v[64:67], v[174:177], v[206:209], v[64:67]
	s_setprio 0
	s_barrier
	s_and_b32 s25, s22, 0xffff
	s_mov_b32 m0, s8
	s_mov_b32 s26, s18
	s_mov_b32 s27, s19
	s_add_u32 s16, s24, 0x4000
	ds_read_b128 v[178:181], v142 offset:16384
	ds_read_b128 v[182:185], v142 offset:17408
	ds_read_b128 v[186:189], v142 offset:18432
	ds_read_b128 v[190:193], v142 offset:19456
	ds_read_b128 v[194:197], v142 offset:20480
	ds_read_b128 v[198:201], v142 offset:21504
	ds_read_b128 v[202:205], v142 offset:22528
	ds_read_b128 v[206:209], v142 offset:23552
	buffer_load_dwordx4 v137, s[24:27], 0 offen lds
	s_mov_b32 m0, s9
	s_addc_u32 s17, s22, 0
	buffer_load_dwordx4 v139, s[24:27], 0 offen lds
	s_and_b32 s17, s17, 0xffff
	s_mov_b32 m0, s76
	s_and_b32 s29, s23, 0xffff
	buffer_load_dwordx4 v137, s[16:19], 0 offen lds
	s_mov_b32 m0, s79
	s_mov_b32 s30, s18
	buffer_load_dwordx4 v139, s[16:19], 0 offen lds
	s_mov_b32 s31, s19
	s_mov_b32 m0, s3
	s_nop 0
	buffer_load_dwordx4 v136, s[28:31], 0 offen lds
	s_mov_b32 m0, s80
	s_nop 0
	buffer_load_dwordx4 v138, s[28:31], 0 offen lds
	s_waitcnt vmcnt(8)
	s_waitcnt lgkmcnt(0)
	s_barrier
; #define PG8_STAGE(bufoff, gbase, voff) do { const __amdgpu_buffer_rsrc_t _rs = __builtin_amdgcn_make_buffer_rsrc((void*)(gbase), 0, 0x7fffffff, 0x00020000); _Pragma("unroll") for (int _i = 0; _i < 2; ++_i) \
;         __builtin_amdgcn_raw_ptr_buffer_load_lds(_rs, (LAS unsigned*)(lds + (bufoff) + ldsw + _i * 8192), 16, (int)(voff)[_i], 0, 0, 0); } while (0)
; #define PG8_WAIT_V(n) asm volatile("s_waitcnt vmcnt(" #n ")" ::: "memory")
; #define PG8_WAIT_L(n) asm volatile("s_waitcnt lgkmcnt(" #n ")" ::: "memory")
; #define PG8_BAR __builtin_amdgcn_s_barrier()
; #define PG8_SCHED __builtin_amdgcn_sched_barrier(0)
; template <class Epi, class Sched, bool F8 = false>
; __device__ __forceinline__ void gemm_phase(LAS unsigned char* lds, const int lda, const int ldb, const Sched& S, const Epi& E) {
;     ...
;             PG8_WAIT_V(8); PG8_WAIT_L(0); PG8_BAR; PG8_MMA(1, 0, At, B0); PG8_MMA(1, 1, At, B1); PG8_BAR; PG8_SCHED;
;             PG8_LDB(B0, 1, 0); PG8_LDB(B1, 1, 1); PG8_SCHED; PG8_LDA(At, 1, 0); PG8_STAGE(PG8_SA(0, 1), a2 + hstepA, voffA);
;             PG8_WAIT_V(8); PG8_WAIT_L(0); PG8_BAR; PG8_MMA(0, 0, At, B0); PG8_MMA(0, 1, At, B1); PG8_BAR; PG8_SCHED;
	s_setprio 1
	v_mfma_f32_16x16x32_bf16 v[60:63], v[132:135], v[178:181], v[60:63]
	v_mfma_f32_16x16x32_bf16 v[56:59], v[150:153], v[178:181], v[56:59]
	v_mfma_f32_16x16x32_bf16 v[44:47], v[132:135], v[186:189], v[44:47]
	v_mfma_f32_16x16x32_bf16 v[40:43], v[150:153], v[186:189], v[40:43]
	v_mfma_f32_16x16x32_bf16 v[28:31], v[132:135], v[194:197], v[28:31]
	v_mfma_f32_16x16x32_bf16 v[24:27], v[150:153], v[194:197], v[24:27]
	v_mfma_f32_16x16x32_bf16 v[12:15], v[132:135], v[202:205], v[12:15]
	v_mfma_f32_16x16x32_bf16 v[8:11], v[150:153], v[202:205], v[8:11]
	v_mfma_f32_16x16x32_bf16 v[60:63], v[146:149], v[182:185], v[60:63]
	v_mfma_f32_16x16x32_bf16 v[56:59], v[154:157], v[182:185], v[56:59]
	v_mfma_f32_16x16x32_bf16 v[44:47], v[146:149], v[190:193], v[44:47]
	v_mfma_f32_16x16x32_bf16 v[40:43], v[154:157], v[190:193], v[40:43]
	v_mfma_f32_16x16x32_bf16 v[28:31], v[146:149], v[198:201], v[28:31]
	v_mfma_f32_16x16x32_bf16 v[24:27], v[154:157], v[198:201], v[24:27]
	v_mfma_f32_16x16x32_bf16 v[12:15], v[146:149], v[206:209], v[12:15]
	v_mfma_f32_16x16x32_bf16 v[8:11], v[154:157], v[206:209], v[8:11]
	s_setprio 0
	s_setprio 1
	v_mfma_f32_16x16x32_bf16 v[52:55], v[158:161], v[178:181], v[52:55]
	v_mfma_f32_16x16x32_bf16 v[48:51], v[166:169], v[178:181], v[48:51]
	v_mfma_f32_16x16x32_bf16 v[36:39], v[158:161], v[186:189], v[36:39]
	v_mfma_f32_16x16x32_bf16 v[32:35], v[166:169], v[186:189], v[32:35]
	v_mfma_f32_16x16x32_bf16 v[20:23], v[158:161], v[194:197], v[20:23]
	v_mfma_f32_16x16x32_bf16 v[16:19], v[166:169], v[194:197], v[16:19]
	v_mfma_f32_16x16x32_bf16 v[4:7], v[158:161], v[202:205], v[4:7]
	v_mfma_f32_16x16x32_bf16 v[0:3], v[166:169], v[202:205], v[0:3]
	v_mfma_f32_16x16x32_bf16 v[52:55], v[162:165], v[182:185], v[52:55]
	v_mfma_f32_16x16x32_bf16 v[48:51], v[174:177], v[182:185], v[48:51]
	v_mfma_f32_16x16x32_bf16 v[36:39], v[162:165], v[190:193], v[36:39]
	v_mfma_f32_16x16x32_bf16 v[32:35], v[174:177], v[190:193], v[32:35]
	v_mfma_f32_16x16x32_bf16 v[20:23], v[162:165], v[198:201], v[20:23]
	v_mfma_f32_16x16x32_bf16 v[16:19], v[174:177], v[198:201], v[16:19]
	v_mfma_f32_16x16x32_bf16 v[4:7], v[162:165], v[206:209], v[4:7]
	v_mfma_f32_16x16x32_bf16 v[0:3], v[174:177], v[206:209], v[0:3]
	s_setprio 0
	s_barrier
	ds_read_b128 v[132:135], v143
	ds_read_b128 v[146:149], v143 offset:1024
	ds_read_b128 v[150:153], v143 offset:2048
	ds_read_b128 v[154:157], v143 offset:3072
	ds_read_b128 v[158:161], v144
	ds_read_b128 v[162:165], v144 offset:1024
	ds_read_b128 v[166:169], v144 offset:2048
	ds_read_b128 v[174:177], v144 offset:3072
	s_add_u32 s16, s28, 0x100000
	s_addc_u32 s17, s23, 0
	s_and_b32 s17, s17, 0xffff
	s_mov_b32 m0, s81
	ds_read_b128 v[178:181], v142 offset:32768
	ds_read_b128 v[182:185], v142 offset:33792
	ds_read_b128 v[186:189], v142 offset:34816
	ds_read_b128 v[190:193], v142 offset:35840
	ds_read_b128 v[194:197], v142 offset:36864
	ds_read_b128 v[198:201], v142 offset:37888
	ds_read_b128 v[202:205], v142 offset:38912
	ds_read_b128 v[206:209], v142 offset:39936
	buffer_load_dwordx4 v136, s[16:19], 0 offen lds
	s_mov_b32 m0, s82
	s_nop 0
	buffer_load_dwordx4 v138, s[16:19], 0 offen lds
	s_waitcnt vmcnt(8)
	s_waitcnt lgkmcnt(0)
	s_barrier
	s_setprio 1
	v_mfma_f32_16x16x32_bf16 v[124:127], v[132:135], v[178:181], v[124:127]
	v_mfma_f32_16x16x32_bf16 v[120:123], v[150:153], v[178:181], v[120:123]
	v_mfma_f32_16x16x32_bf16 v[108:111], v[132:135], v[186:189], v[108:111]
	v_mfma_f32_16x16x32_bf16 v[104:107], v[150:153], v[186:189], v[104:107]
	v_mfma_f32_16x16x32_bf16 v[92:95], v[132:135], v[194:197], v[92:95]
	v_mfma_f32_16x16x32_bf16 v[88:91], v[150:153], v[194:197], v[88:91]
	v_mfma_f32_16x16x32_bf16 v[76:79], v[132:135], v[202:205], v[76:79]
	v_mfma_f32_16x16x32_bf16 v[72:75], v[150:153], v[202:205], v[72:75]
	v_mfma_f32_16x16x32_bf16 v[124:127], v[146:149], v[182:185], v[124:127]
	v_mfma_f32_16x16x32_bf16 v[120:123], v[154:157], v[182:185], v[120:123]
	v_mfma_f32_16x16x32_bf16 v[108:111], v[146:149], v[190:193], v[108:111]
	v_mfma_f32_16x16x32_bf16 v[104:107], v[154:157], v[190:193], v[104:107]
	v_mfma_f32_16x16x32_bf16 v[92:95], v[146:149], v[198:201], v[92:95]
	v_mfma_f32_16x16x32_bf16 v[88:91], v[154:157], v[198:201], v[88:91]
	v_mfma_f32_16x16x32_bf16 v[76:79], v[146:149], v[206:209], v[76:79]
	v_mfma_f32_16x16x32_bf16 v[72:75], v[154:157], v[206:209], v[72:75]
	s_setprio 0
	s_setprio 1
	v_mfma_f32_16x16x32_bf16 v[116:119], v[158:161], v[178:181], v[116:119]
	v_mfma_f32_16x16x32_bf16 v[112:115], v[166:169], v[178:181], v[112:115]
	v_mfma_f32_16x16x32_bf16 v[100:103], v[158:161], v[186:189], v[100:103]
	v_mfma_f32_16x16x32_bf16 v[96:99], v[166:169], v[186:189], v[96:99]
	v_mfma_f32_16x16x32_bf16 v[84:87], v[158:161], v[194:197], v[84:87]
	v_mfma_f32_16x16x32_bf16 v[80:83], v[166:169], v[194:197], v[80:83]
	v_mfma_f32_16x16x32_bf16 v[68:71], v[158:161], v[202:205], v[68:71]
	v_mfma_f32_16x16x32_bf16 v[64:67], v[166:169], v[202:205], v[64:67]
	v_mfma_f32_16x16x32_bf16 v[116:119], v[162:165], v[182:185], v[116:119]
	v_mfma_f32_16x16x32_bf16 v[112:115], v[174:177], v[182:185], v[112:115]
	v_mfma_f32_16x16x32_bf16 v[100:103], v[162:165], v[190:193], v[100:103]
	v_mfma_f32_16x16x32_bf16 v[96:99], v[174:177], v[190:193], v[96:99]
	v_mfma_f32_16x16x32_bf16 v[84:87], v[162:165], v[198:201], v[84:87]
	v_mfma_f32_16x16x32_bf16 v[80:83], v[174:177], v[198:201], v[80:83]
	v_mfma_f32_16x16x32_bf16 v[68:71], v[162:165], v[206:209], v[68:71]
	v_mfma_f32_16x16x32_bf16 v[64:67], v[174:177], v[206:209], v[64:67]
	s_setprio 0
	s_barrier
; #define PG8_STAGE(bufoff, gbase, voff) do { const __amdgpu_buffer_rsrc_t _rs = __builtin_amdgcn_make_buffer_rsrc((void*)(gbase), 0, 0x7fffffff, 0x00020000); _Pragma("unroll") for (int _i = 0; _i < 2; ++_i) \
;         __builtin_amdgcn_raw_ptr_buffer_load_lds(_rs, (LAS unsigned*)(lds + (bufoff) + ldsw + _i * 8192), 16, (int)(voff)[_i], 0, 0, 0); } while (0)
; #define PG8_WAIT_V(n) asm volatile("s_waitcnt vmcnt(" #n ")" ::: "memory")
; #define PG8_WAIT_L(n) asm volatile("s_waitcnt lgkmcnt(" #n ")" ::: "memory")
; #define PG8_BAR __builtin_amdgcn_s_barrier()
; #define PG8_SCHED __builtin_amdgcn_sched_barrier(0)
; template <class Epi, class Sched, bool F8 = false>
; __device__ __forceinline__ void gemm_phase(LAS unsigned char* lds, const int lda, const int ldb, const Sched& S, const Epi& E) {
;     ...
;             PG8_LDA(At, 1, 1); PG8_STAGE(PG8_SB(1, 0), b3, voffB); PG8_STAGE(PG8_SB(1, 1), b3 + hstepB, voffB); PG8_STAGE(PG8_SA(1, 0), a3, voffA);
;             PG8_WAIT_V(8); PG8_WAIT_L(0); PG8_BAR; PG8_MMA(1, 0, At, B0); PG8_MMA(1, 1, At, B1); PG8_BAR; PG8_SCHED;
	s_add_u32 s16, s24, 0x8000
	s_addc_u32 s17, s22, 0
	s_mov_b32 m0, s87
	s_and_b32 s17, s17, 0xffff
	ds_read_b128 v[178:181], v142 offset:49152
	ds_read_b128 v[182:185], v142 offset:50176
	ds_read_b128 v[186:189], v142 offset:51200
	ds_read_b128 v[190:193], v142 offset:52224
	ds_read_b128 v[194:197], v142 offset:53248
	ds_read_b128 v[198:201], v142 offset:54272
	ds_read_b128 v[202:205], v142 offset:55296
	ds_read_b128 v[206:209], v142 offset:56320
	buffer_load_dwordx4 v137, s[16:19], 0 offen lds
	s_mov_b32 m0, s88
	s_mov_b32 s23, s19
	buffer_load_dwordx4 v139, s[16:19], 0 offen lds
	s_add_u32 s16, s24, 0xc000
	s_addc_u32 s17, s22, 0
	s_and_b32 s17, s17, 0xffff
	s_mov_b32 m0, s91
	s_and_b32 s21, s21, 0xffff
	buffer_load_dwordx4 v137, s[16:19], 0 offen lds
	s_mov_b32 m0, s92
	s_mov_b32 s22, s18
	buffer_load_dwordx4 v139, s[16:19], 0 offen lds
	s_mov_b32 m0, s89
	s_nop 0
	buffer_load_dwordx4 v136, s[20:23], 0 offen lds
	s_mov_b32 m0, s90
	s_nop 0
	buffer_load_dwordx4 v138, s[20:23], 0 offen lds
	s_waitcnt vmcnt(8)
	s_waitcnt lgkmcnt(0)
	s_barrier
	s_setprio 1
	v_mfma_f32_16x16x32_bf16 v[60:63], v[132:135], v[178:181], v[60:63]
	v_mfma_f32_16x16x32_bf16 v[56:59], v[150:153], v[178:181], v[56:59]
	v_mfma_f32_16x16x32_bf16 v[44:47], v[132:135], v[186:189], v[44:47]
	v_mfma_f32_16x16x32_bf16 v[40:43], v[150:153], v[186:189], v[40:43]
	v_mfma_f32_16x16x32_bf16 v[28:31], v[132:135], v[194:197], v[28:31]
	v_mfma_f32_16x16x32_bf16 v[24:27], v[150:153], v[194:197], v[24:27]
	v_mfma_f32_16x16x32_bf16 v[12:15], v[132:135], v[202:205], v[12:15]
	v_mfma_f32_16x16x32_bf16 v[8:11], v[150:153], v[202:205], v[8:11]
	v_mfma_f32_16x16x32_bf16 v[60:63], v[146:149], v[182:185], v[60:63]
	v_mfma_f32_16x16x32_bf16 v[56:59], v[154:157], v[182:185], v[56:59]
	v_mfma_f32_16x16x32_bf16 v[44:47], v[146:149], v[190:193], v[44:47]
	v_mfma_f32_16x16x32_bf16 v[40:43], v[154:157], v[190:193], v[40:43]
	v_mfma_f32_16x16x32_bf16 v[28:31], v[146:149], v[198:201], v[28:31]
	v_mfma_f32_16x16x32_bf16 v[24:27], v[154:157], v[198:201], v[24:27]
	v_mfma_f32_16x16x32_bf16 v[12:15], v[146:149], v[206:209], v[12:15]
	v_mfma_f32_16x16x32_bf16 v[8:11], v[154:157], v[206:209], v[8:11]
	s_setprio 0
	s_setprio 1
	v_mfma_f32_16x16x32_bf16 v[52:55], v[158:161], v[178:181], v[52:55]
	v_mfma_f32_16x16x32_bf16 v[48:51], v[166:169], v[178:181], v[48:51]
	v_mfma_f32_16x16x32_bf16 v[36:39], v[158:161], v[186:189], v[36:39]
	v_mfma_f32_16x16x32_bf16 v[32:35], v[166:169], v[186:189], v[32:35]
	v_mfma_f32_16x16x32_bf16 v[20:23], v[158:161], v[194:197], v[20:23]
	v_mfma_f32_16x16x32_bf16 v[16:19], v[166:169], v[194:197], v[16:19]
	v_mfma_f32_16x16x32_bf16 v[4:7], v[158:161], v[202:205], v[4:7]
	v_mfma_f32_16x16x32_bf16 v[0:3], v[166:169], v[202:205], v[0:3]
	v_mfma_f32_16x16x32_bf16 v[52:55], v[162:165], v[182:185], v[52:55]
	v_mfma_f32_16x16x32_bf16 v[48:51], v[174:177], v[182:185], v[48:51]
	v_mfma_f32_16x16x32_bf16 v[36:39], v[162:165], v[190:193], v[36:39]
	v_mfma_f32_16x16x32_bf16 v[32:35], v[174:177], v[190:193], v[32:35]
	v_mfma_f32_16x16x32_bf16 v[20:23], v[162:165], v[198:201], v[20:23]
	v_mfma_f32_16x16x32_bf16 v[16:19], v[174:177], v[198:201], v[16:19]
	v_mfma_f32_16x16x32_bf16 v[4:7], v[162:165], v[206:209], v[4:7]
	v_mfma_f32_16x16x32_bf16 v[0:3], v[174:177], v[206:209], v[0:3]
	s_setprio 0
	s_barrier
	s_add_i32 s69, s69, 2
	s_add_u32 s7, s7, 0x10000
	s_addc_u32 s62, s62, 0
	s_add_u32 s63, s63, 0x100
	s_addc_u32 s67, s67, 0
	s_cmp_gt_u32 s69, 61
	s_cbranch_scc0 .LBB0_116
	s_and_b64 vcc, exec, s[38:39]
	s_cbranch_vccz .LBB0_119
	s_barrier

; #define PG8_STAGE(bufoff, gbase, voff) do { const __amdgpu_buffer_rsrc_t _rs = __builtin_amdgcn_make_buffer_rsrc((void*)(gbase), 0, 0x7fffffff, 0x00020000); _Pragma("unroll") for (int _i = 0; _i < 2; ++_i) \
;         __builtin_amdgcn_raw_ptr_buffer_load_lds(_rs, (LAS unsigned*)(lds + (bufoff) + ldsw + _i * 8192), 16, (int)(voff)[_i], 0, 0, 0); } while (0)
; #define PG8_WAIT_V(n) asm volatile("s_waitcnt vmcnt(" #n ")" ::: "memory")
; #define PG8_WAIT_L(n) asm volatile("s_waitcnt lgkmcnt(" #n ")" ::: "memory")
; #define PG8_BAR __builtin_amdgcn_s_barrier()
; #define PG8_SCHED __builtin_amdgcn_sched_barrier(0)
; template <class Epi, class Sched, bool F8 = false>
; __device__ __forceinline__ void gemm_phase(LAS unsigned char* lds, const int lda, const int ldb, const Sched& S, const Epi& E) {
;     ...
;             const bool last = (t == nt - 2);
;             const char* a1 = cA + (size_t)(t + 1) * kstep;
;             const char* a2 = last ? nA : cA + (size_t)(t + 2) * kstep; const char* b2 = last ? nB : cB + (size_t)(t + 2) * kstepB;
;             const char* a3 = a2 + kstep; const char* b3 = b2 + kstepB;
;     ...
;             PG8_LDB(B0, 0, 0); PG8_LDB(B1, 0, 1); PG8_SCHED; PG8_LDA(At, 0, 0); PG8_STAGE(PG8_SA(1, 1), a1 + hstepA, voffA);
;             PG8_WAIT_V(8); PG8_WAIT_L(0); PG8_BAR; PG8_MMA(0, 0, At, B0); PG8_MMA(0, 1, At, B1); PG8_BAR; PG8_SCHED;
;             PG8_LDA(At, 0, 1); PG8_STAGE(PG8_SB(0, 0), b2, voffB); PG8_STAGE(PG8_SB(0, 1), b2 + hstepB, voffB); PG8_STAGE(PG8_SA(0, 0), a2, voffA);
;             PG8_WAIT_V(8); PG8_WAIT_L(0); PG8_BAR; PG8_MMA(1, 0, At, B0); PG8_MMA(1, 1, At, B1); PG8_BAR; PG8_SCHED;
.LBB0_174:
	ds_read_b128 v[146:149], v140
	ds_read_b128 v[150:153], v140 offset:1024
	ds_read_b128 v[154:157], v140 offset:2048
	ds_read_b128 v[158:161], v140 offset:3072
	ds_read_b128 v[162:165], v141
	ds_read_b128 v[166:169], v141 offset:1024
	ds_read_b128 v[174:177], v141 offset:2048
	ds_read_b128 v[178:181], v141 offset:3072
	s_add_u32 s16, s63, 0xfff80080
	s_addc_u32 s17, s67, -1
	s_cmp_eq_u32 s69, 28
	s_cselect_b32 s28, s70, s16
	s_cselect_b32 s23, s71, s17
	s_cselect_b32 s22, s73, s62
	s_cselect_b32 s24, s72, s7
	s_add_u32 s20, s28, 0x80
	s_addc_u32 s21, s23, 0
	s_and_b32 s17, s67, 0xffff
	s_mov_b32 s16, s63
	s_mov_b32 m0, s96
	ds_read_b128 v[182:185], v142
	ds_read_b128 v[186:189], v142 offset:1024
	ds_read_b128 v[190:193], v142 offset:2048
	ds_read_b128 v[194:197], v142 offset:3072
	ds_read_b128 v[198:201], v142 offset:4096
	ds_read_b128 v[202:205], v142 offset:5120
	ds_read_b128 v[206:209], v142 offset:6144
	ds_read_b128 v[210:213], v142 offset:7168
	buffer_load_dwordx4 v136, s[16:19], 0 offen lds
	s_mov_b32 m0, s97
	s_nop 0
	buffer_load_dwordx4 v138, s[16:19], 0 offen lds
	s_waitcnt vmcnt(8)
	s_waitcnt lgkmcnt(0)
	s_barrier
	s_setprio 1
	v_mfma_scale_f32_16x16x128_f8f6f4 v[124:127], v[146:153], v[182:189], v[124:127], v143, v143 op_sel_hi:[0,0,0]
	v_mfma_scale_f32_16x16x128_f8f6f4 v[120:123], v[154:161], v[182:189], v[120:123], v143, v143 op_sel_hi:[0,0,0]
	v_mfma_scale_f32_16x16x128_f8f6f4 v[108:111], v[146:153], v[190:197], v[108:111], v143, v143 op_sel_hi:[0,0,0]
	v_mfma_scale_f32_16x16x128_f8f6f4 v[104:107], v[154:161], v[190:197], v[104:107], v143, v143 op_sel_hi:[0,0,0]
	v_mfma_scale_f32_16x16x128_f8f6f4 v[132:135], v[146:153], v[198:205], v[92:95], v143, v143 op_sel_hi:[0,0,0]
	v_mfma_scale_f32_16x16x128_f8f6f4 v[214:217], v[154:161], v[198:205], v[88:91], v143, v143 op_sel_hi:[0,0,0]
	v_mfma_scale_f32_16x16x128_f8f6f4 v[218:221], v[146:153], v[206:213], v[76:79], v143, v143 op_sel_hi:[0,0,0]
	v_mfma_scale_f32_16x16x128_f8f6f4 v[222:225], v[154:161], v[206:213], v[72:75], v143, v143 op_sel_hi:[0,0,0]
	s_setprio 0
	s_setprio 1
	v_mfma_scale_f32_16x16x128_f8f6f4 v[116:119], v[162:169], v[182:189], v[116:119], v143, v143 op_sel_hi:[0,0,0]
	v_mfma_scale_f32_16x16x128_f8f6f4 v[112:115], v[174:181], v[182:189], v[112:115], v143, v143 op_sel_hi:[0,0,0]
	v_mfma_scale_f32_16x16x128_f8f6f4 v[100:103], v[162:169], v[190:197], v[100:103], v143, v143 op_sel_hi:[0,0,0]
	v_mfma_scale_f32_16x16x128_f8f6f4 v[96:99], v[174:181], v[190:197], v[96:99], v143, v143 op_sel_hi:[0,0,0]
	v_mfma_scale_f32_16x16x128_f8f6f4 v[182:185], v[162:169], v[198:205], v[84:87], v143, v143 op_sel_hi:[0,0,0]
	v_mfma_scale_f32_16x16x128_f8f6f4 v[186:189], v[174:181], v[198:205], v[80:83], v143, v143 op_sel_hi:[0,0,0]
	v_mfma_scale_f32_16x16x128_f8f6f4 v[190:193], v[162:169], v[206:213], v[68:71], v143, v143 op_sel_hi:[0,0,0]
	v_mfma_scale_f32_16x16x128_f8f6f4 v[194:197], v[174:181], v[206:213], v[64:67], v143, v143 op_sel_hi:[0,0,0]
	s_setprio 0
	s_barrier
	s_and_b32 s25, s22, 0xffff
	s_mov_b32 m0, s79
	s_mov_b32 s26, s18
	s_mov_b32 s27, s19
	s_add_u32 s16, s24, 0x4000
	ds_read_b128 v[64:67], v142 offset:16384
	ds_read_b128 v[68:71], v142 offset:17408
	ds_read_b128 v[72:75], v142 offset:18432
	ds_read_b128 v[76:79], v142 offset:19456
	ds_read_b128 v[80:83], v142 offset:20480
	ds_read_b128 v[84:87], v142 offset:21504
	ds_read_b128 v[88:91], v142 offset:22528
	ds_read_b128 v[92:95], v142 offset:23552
	buffer_load_dwordx4 v137, s[24:27], 0 offen lds
	s_mov_b32 m0, s80
	s_addc_u32 s17, s22, 0
	buffer_load_dwordx4 v139, s[24:27], 0 offen lds
	s_and_b32 s17, s17, 0xffff
	s_mov_b32 m0, s81
	s_and_b32 s29, s23, 0xffff
	buffer_load_dwordx4 v137, s[16:19], 0 offen lds
	s_mov_b32 m0, s82
	s_mov_b32 s30, s18
	buffer_load_dwordx4 v139, s[16:19], 0 offen lds
	s_mov_b32 s31, s19
	s_mov_b32 m0, s76
	s_nop 0
	buffer_load_dwordx4 v136, s[28:31], 0 offen lds
	s_mov_b32 m0, s83
	s_nop 0
	buffer_load_dwordx4 v138, s[28:31], 0 offen lds
	s_waitcnt vmcnt(8)
	s_waitcnt lgkmcnt(0)
	s_barrier
	s_setprio 1
	v_mfma_scale_f32_16x16x128_f8f6f4 v[60:63], v[146:153], v[64:71], v[60:63], v143, v143 op_sel_hi:[0,0,0]
	v_mfma_scale_f32_16x16x128_f8f6f4 v[56:59], v[154:161], v[64:71], v[56:59], v143, v143 op_sel_hi:[0,0,0]
	v_mfma_scale_f32_16x16x128_f8f6f4 v[198:201], v[146:153], v[72:79], v[44:47], v143, v143 op_sel_hi:[0,0,0]
	v_mfma_scale_f32_16x16x128_f8f6f4 v[202:205], v[154:161], v[72:79], v[40:43], v143, v143 op_sel_hi:[0,0,0]
	v_mfma_scale_f32_16x16x128_f8f6f4 v[206:209], v[146:153], v[80:87], v[28:31], v143, v143 op_sel_hi:[0,0,0]
	v_mfma_scale_f32_16x16x128_f8f6f4 v[210:213], v[154:161], v[80:87], v[24:27], v143, v143 op_sel_hi:[0,0,0]
	v_mfma_scale_f32_16x16x128_f8f6f4 v[226:229], v[146:153], v[88:95], v[12:15], v143, v143 op_sel_hi:[0,0,0]
	v_mfma_scale_f32_16x16x128_f8f6f4 v[230:233], v[154:161], v[88:95], v[8:11], v143, v143 op_sel_hi:[0,0,0]
	s_setprio 0
	s_setprio 1
	v_mfma_scale_f32_16x16x128_f8f6f4 v[52:55], v[162:169], v[64:71], v[52:55], v143, v143 op_sel_hi:[0,0,0]
	v_mfma_scale_f32_16x16x128_f8f6f4 v[48:51], v[174:181], v[64:71], v[48:51], v143, v143 op_sel_hi:[0,0,0]
	v_mfma_scale_f32_16x16x128_f8f6f4 v[234:237], v[162:169], v[72:79], v[36:39], v143, v143 op_sel_hi:[0,0,0]
	v_mfma_scale_f32_16x16x128_f8f6f4 v[238:241], v[174:181], v[72:79], v[32:35], v143, v143 op_sel_hi:[0,0,0]
	v_mfma_scale_f32_16x16x128_f8f6f4 v[242:245], v[162:169], v[80:87], v[20:23], v143, v143 op_sel_hi:[0,0,0]
	v_mfma_scale_f32_16x16x128_f8f6f4 v[246:249], v[174:181], v[80:87], v[16:19], v143, v143 op_sel_hi:[0,0,0]
	v_mfma_scale_f32_16x16x128_f8f6f4 v[250:253], v[162:169], v[88:95], v[4:7], v143, v143 op_sel_hi:[0,0,0]
	v_mfma_scale_f32_16x16x128_f8f6f4 v[170:173], v[174:181], v[88:95], v[0:3], v143, v143 op_sel_hi:[0,0,0]
	s_setprio 0
	s_barrier
; #define PG8_STAGE(bufoff, gbase, voff) do { const __amdgpu_buffer_rsrc_t _rs = __builtin_amdgcn_make_buffer_rsrc((void*)(gbase), 0, 0x7fffffff, 0x00020000); _Pragma("unroll") for (int _i = 0; _i < 2; ++_i) \
;         __builtin_amdgcn_raw_ptr_buffer_load_lds(_rs, (LAS unsigned*)(lds + (bufoff) + ldsw + _i * 8192), 16, (int)(voff)[_i], 0, 0, 0); } while (0)
; #define PG8_WAIT_V(n) asm volatile("s_waitcnt vmcnt(" #n ")" ::: "memory")
; #define PG8_WAIT_L(n) asm volatile("s_waitcnt lgkmcnt(" #n ")" ::: "memory")
; #define PG8_BAR __builtin_amdgcn_s_barrier()
; #define PG8_SCHED __builtin_amdgcn_sched_barrier(0)
; template <class Epi, class Sched, bool F8 = false>
; __device__ __forceinline__ void gemm_phase(LAS unsigned char* lds, const int lda, const int ldb, const Sched& S, const Epi& E) {
;     ...
;             PG8_LDB(B0, 1, 0); PG8_LDB(B1, 1, 1); PG8_SCHED; PG8_LDA(At, 1, 0); PG8_STAGE(PG8_SA(0, 1), a2 + hstepA, voffA);
;             PG8_WAIT_V(8); PG8_WAIT_L(0); PG8_BAR; PG8_MMA(0, 0, At, B0); PG8_MMA(0, 1, At, B1); PG8_BAR; PG8_SCHED;
;             PG8_LDA(At, 1, 1); PG8_STAGE(PG8_SB(1, 0), b3, voffB); PG8_STAGE(PG8_SB(1, 1), b3 + hstepB, voffB); PG8_STAGE(PG8_SA(1, 0), a3, voffA);
;             PG8_WAIT_V(8); PG8_WAIT_L(0); PG8_BAR; PG8_MMA(1, 0, At, B0); PG8_MMA(1, 1, At, B1); PG8_BAR; PG8_SCHED;
	s_nop 4
	ds_read_b128 v[0:3], v144
	ds_read_b128 v[4:7], v144 offset:1024
	ds_read_b128 v[16:19], v144 offset:2048
	ds_read_b128 v[20:23], v144 offset:3072
	ds_read_b128 v[146:149], v145
	ds_read_b128 v[150:153], v145 offset:1024
	ds_read_b128 v[154:157], v145 offset:2048
	ds_read_b128 v[158:161], v145 offset:3072
	s_add_u32 s16, s28, 0x80000
	s_addc_u32 s17, s23, 0
	s_and_b32 s17, s17, 0xffff
	s_mov_b32 m0, s84
	ds_read_b128 v[8:11], v142 offset:32768
	ds_read_b128 v[12:15], v142 offset:33792
	ds_read_b128 v[24:27], v142 offset:34816
	ds_read_b128 v[28:31], v142 offset:35840
	ds_read_b128 v[32:35], v142 offset:36864
	ds_read_b128 v[36:39], v142 offset:37888
	ds_read_b128 v[40:43], v142 offset:38912
	ds_read_b128 v[44:47], v142 offset:39936
	buffer_load_dwordx4 v136, s[16:19], 0 offen lds
	s_mov_b32 m0, s85
	s_nop 0
	buffer_load_dwordx4 v138, s[16:19], 0 offen lds
	s_waitcnt vmcnt(8)
	s_waitcnt lgkmcnt(0)
	s_barrier
	s_setprio 1
	v_mfma_scale_f32_16x16x128_f8f6f4 v[124:127], v[0:7], v[8:15], v[124:127], v143, v143 op_sel_hi:[0,0,0]
	v_mfma_scale_f32_16x16x128_f8f6f4 v[120:123], v[16:23], v[8:15], v[120:123], v143, v143 op_sel_hi:[0,0,0]
	v_mfma_scale_f32_16x16x128_f8f6f4 v[108:111], v[0:7], v[24:31], v[108:111], v143, v143 op_sel_hi:[0,0,0]
	v_mfma_scale_f32_16x16x128_f8f6f4 v[104:107], v[16:23], v[24:31], v[104:107], v143, v143 op_sel_hi:[0,0,0]
	v_mfma_scale_f32_16x16x128_f8f6f4 v[92:95], v[0:7], v[32:39], v[132:135], v143, v143 op_sel_hi:[0,0,0]
	v_mfma_scale_f32_16x16x128_f8f6f4 v[88:91], v[16:23], v[32:39], v[214:217], v143, v143 op_sel_hi:[0,0,0]
	v_mfma_scale_f32_16x16x128_f8f6f4 v[76:79], v[0:7], v[40:47], v[218:221], v143, v143 op_sel_hi:[0,0,0]
	v_mfma_scale_f32_16x16x128_f8f6f4 v[72:75], v[16:23], v[40:47], v[222:225], v143, v143 op_sel_hi:[0,0,0]
	s_setprio 0
	s_setprio 1
	v_mfma_scale_f32_16x16x128_f8f6f4 v[116:119], v[146:153], v[8:15], v[116:119], v143, v143 op_sel_hi:[0,0,0]
	v_mfma_scale_f32_16x16x128_f8f6f4 v[112:115], v[154:161], v[8:15], v[112:115], v143, v143 op_sel_hi:[0,0,0]
	v_mfma_scale_f32_16x16x128_f8f6f4 v[100:103], v[146:153], v[24:31], v[100:103], v143, v143 op_sel_hi:[0,0,0]
	v_mfma_scale_f32_16x16x128_f8f6f4 v[96:99], v[154:161], v[24:31], v[96:99], v143, v143 op_sel_hi:[0,0,0]
	v_mfma_scale_f32_16x16x128_f8f6f4 v[84:87], v[146:153], v[32:39], v[182:185], v143, v143 op_sel_hi:[0,0,0]
	v_mfma_scale_f32_16x16x128_f8f6f4 v[80:83], v[154:161], v[32:39], v[186:189], v143, v143 op_sel_hi:[0,0,0]
	v_mfma_scale_f32_16x16x128_f8f6f4 v[68:71], v[146:153], v[40:47], v[190:193], v143, v143 op_sel_hi:[0,0,0]
	v_mfma_scale_f32_16x16x128_f8f6f4 v[64:67], v[154:161], v[40:47], v[194:197], v143, v143 op_sel_hi:[0,0,0]
	s_setprio 0
	s_barrier
	s_add_u32 s16, s24, 0x8000
	s_addc_u32 s17, s22, 0
	s_mov_b32 m0, s90
	s_and_b32 s17, s17, 0xffff
	ds_read_b128 v[32:35], v142 offset:49152
	ds_read_b128 v[36:39], v142 offset:50176
	ds_read_b128 v[162:165], v142 offset:51200
	ds_read_b128 v[166:169], v142 offset:52224
	ds_read_b128 v[174:177], v142 offset:53248
	ds_read_b128 v[178:181], v142 offset:54272
	ds_read_b128 v[182:185], v142 offset:55296
	ds_read_b128 v[186:189], v142 offset:56320
	buffer_load_dwordx4 v137, s[16:19], 0 offen lds
	s_mov_b32 m0, s91
	s_mov_b32 s23, s19
	buffer_load_dwordx4 v139, s[16:19], 0 offen lds
	s_add_u32 s16, s24, 0xc000
	s_addc_u32 s17, s22, 0
	s_and_b32 s17, s17, 0xffff
	s_mov_b32 m0, s94
	s_and_b32 s21, s21, 0xffff
	buffer_load_dwordx4 v137, s[16:19], 0 offen lds
	s_mov_b32 m0, s95
	s_mov_b32 s22, s18
	buffer_load_dwordx4 v139, s[16:19], 0 offen lds
	s_mov_b32 m0, s92
	s_nop 0
	buffer_load_dwordx4 v136, s[20:23], 0 offen lds
	s_mov_b32 m0, s93
	s_nop 0
	buffer_load_dwordx4 v138, s[20:23], 0 offen lds
	s_waitcnt vmcnt(8)
	s_waitcnt lgkmcnt(0)
	s_barrier
	s_setprio 1
	v_mfma_scale_f32_16x16x128_f8f6f4 v[60:63], v[0:7], v[32:39], v[60:63], v143, v143 op_sel_hi:[0,0,0]
	v_mfma_scale_f32_16x16x128_f8f6f4 v[56:59], v[16:23], v[32:39], v[56:59], v143, v143 op_sel_hi:[0,0,0]
	v_mfma_scale_f32_16x16x128_f8f6f4 v[44:47], v[0:7], v[162:169], v[198:201], v143, v143 op_sel_hi:[0,0,0]
	v_mfma_scale_f32_16x16x128_f8f6f4 v[40:43], v[16:23], v[162:169], v[202:205], v143, v143 op_sel_hi:[0,0,0]
	v_mfma_scale_f32_16x16x128_f8f6f4 v[28:31], v[0:7], v[174:181], v[206:209], v143, v143 op_sel_hi:[0,0,0]
	v_mfma_scale_f32_16x16x128_f8f6f4 v[24:27], v[16:23], v[174:181], v[210:213], v143, v143 op_sel_hi:[0,0,0]
	v_mfma_scale_f32_16x16x128_f8f6f4 v[12:15], v[0:7], v[182:189], v[226:229], v143, v143 op_sel_hi:[0,0,0]
	v_mfma_scale_f32_16x16x128_f8f6f4 v[8:11], v[16:23], v[182:189], v[230:233], v143, v143 op_sel_hi:[0,0,0]
	s_setprio 0
	s_setprio 1
	v_mfma_scale_f32_16x16x128_f8f6f4 v[52:55], v[146:153], v[32:39], v[52:55], v143, v143 op_sel_hi:[0,0,0]
	v_mfma_scale_f32_16x16x128_f8f6f4 v[48:51], v[154:161], v[32:39], v[48:51], v143, v143 op_sel_hi:[0,0,0]
	v_mfma_scale_f32_16x16x128_f8f6f4 v[36:39], v[146:153], v[162:169], v[234:237], v143, v143 op_sel_hi:[0,0,0]
	v_mfma_scale_f32_16x16x128_f8f6f4 v[32:35], v[154:161], v[162:169], v[238:241], v143, v143 op_sel_hi:[0,0,0]
	v_mfma_scale_f32_16x16x128_f8f6f4 v[20:23], v[146:153], v[174:181], v[242:245], v143, v143 op_sel_hi:[0,0,0]
	v_mfma_scale_f32_16x16x128_f8f6f4 v[16:19], v[154:161], v[174:181], v[246:249], v143, v143 op_sel_hi:[0,0,0]
	v_mfma_scale_f32_16x16x128_f8f6f4 v[4:7], v[146:153], v[182:189], v[250:253], v143, v143 op_sel_hi:[0,0,0]
	v_mfma_scale_f32_16x16x128_f8f6f4 v[0:3], v[154:161], v[182:189], v[170:173], v143, v143 op_sel_hi:[0,0,0]
	s_setprio 0
	s_barrier
	s_add_i32 s69, s69, 2
	s_add_u32 s7, s7, 0x10000
	s_addc_u32 s62, s62, 0
	s_add_u32 s63, s63, 0x100
	s_addc_u32 s67, s67, 0
	s_cmp_gt_u32 s69, 29
	s_cbranch_scc0 .LBB0_174
	s_and_b64 vcc, exec, s[38:39]
	s_cbranch_vccz .LBB0_177
	s_barrier

; #define PG8_STAGE(bufoff, gbase, voff) do { const __amdgpu_buffer_rsrc_t _rs = __builtin_amdgcn_make_buffer_rsrc((void*)(gbase), 0, 0x7fffffff, 0x00020000); _Pragma("unroll") for (int _i = 0; _i < 2; ++_i) \
;         __builtin_amdgcn_raw_ptr_buffer_load_lds(_rs, (LAS unsigned*)(lds + (bufoff) + ldsw + _i * 8192), 16, (int)(voff)[_i], 0, 0, 0); } while (0)
; #define PG8_WAIT_V(n) asm volatile("s_waitcnt vmcnt(" #n ")" ::: "memory")
; #define PG8_WAIT_L(n) asm volatile("s_waitcnt lgkmcnt(" #n ")" ::: "memory")
; #define PG8_BAR __builtin_amdgcn_s_barrier()
; #define PG8_SCHED __builtin_amdgcn_sched_barrier(0)
; template <class Epi, class Sched, bool F8 = false>
; __device__ __forceinline__ void gemm_phase(LAS unsigned char* lds, const int lda, const int ldb, const Sched& S, const Epi& E) {
;     ...
;             const bool last = (t == nt - 2);
;             const char* a1 = cA + (size_t)(t + 1) * kstep;
;             const char* a2 = last ? nA : cA + (size_t)(t + 2) * kstep; const char* b2 = last ? nB : cB + (size_t)(t + 2) * kstepB;
;             const char* a3 = a2 + kstep; const char* b3 = b2 + kstepB;
;     ...
;             PG8_LDB(B0, 0, 0); PG8_LDB(B1, 0, 1); PG8_SCHED; PG8_LDA(At, 0, 0); PG8_STAGE(PG8_SA(1, 1), a1 + hstepA, voffA);
;             PG8_WAIT_V(8); PG8_WAIT_L(0); PG8_BAR; PG8_MMA(0, 0, At, B0); PG8_MMA(0, 1, At, B1); PG8_BAR; PG8_SCHED;
;             PG8_LDA(At, 0, 1); PG8_STAGE(PG8_SB(0, 0), b2, voffB); PG8_STAGE(PG8_SB(0, 1), b2 + hstepB, voffB); PG8_STAGE(PG8_SA(0, 0), a2, voffA);
;             PG8_WAIT_V(8); PG8_WAIT_L(0); PG8_BAR; PG8_MMA(1, 0, At, B0); PG8_MMA(1, 1, At, B1); PG8_BAR; PG8_SCHED;
.LBB0_408:
	ds_read_b128 v[104:107], v180
	ds_read_b128 v[108:111], v180 offset:1024
	ds_read_b128 v[136:139], v180 offset:2048
	ds_read_b128 v[140:143], v180 offset:3072
	ds_read_b128 v[148:151], v181
	ds_read_b128 v[152:155], v181 offset:1024
	ds_read_b128 v[156:159], v181 offset:2048
	ds_read_b128 v[160:163], v181 offset:3072
	s_add_i32 s64, s4, 2
	s_add_u32 s5, vcc_hi, 0xfff80080
	s_addc_u32 s16, s35, -1
	s_cmp_eq_u32 s62, s4
	s_cselect_b32 s40, s70, s5
	s_cselect_b32 s19, s71, s16
	s_cselect_b32 s18, s73, vcc_lo
	s_cselect_b32 s36, s72, s63
	s_add_u32 s16, s40, 0x80
	s_addc_u32 s17, s19, 0
	s_and_b32 s5, s35, 0xffff
	s_mov_b32 s4, vcc_hi
	s_mov_b32 m0, s92
	ds_read_b128 v[164:167], v182
	ds_read_b128 v[168:171], v182 offset:1024
	ds_read_b128 v[172:175], v182 offset:2048
	ds_read_b128 v[186:189], v182 offset:3072
	ds_read_b128 v[190:193], v182 offset:4096
	ds_read_b128 v[194:197], v182 offset:5120
	ds_read_b128 v[198:201], v182 offset:6144
	ds_read_b128 v[202:205], v182 offset:7168
	buffer_load_dwordx4 v176, s[4:7], 0 offen lds
	s_mov_b32 m0, s93
	s_nop 0
	buffer_load_dwordx4 v178, s[4:7], 0 offen lds
	s_waitcnt vmcnt(8)
	s_waitcnt lgkmcnt(0)
	s_barrier
	s_setprio 1
	v_mfma_f32_16x16x32_bf16 v[132:135], v[104:107], v[164:167], v[132:135]
	v_mfma_f32_16x16x32_bf16 v[128:131], v[136:139], v[164:167], v[128:131]
	v_mfma_f32_16x16x32_bf16 v[124:127], v[104:107], v[172:175], v[124:127]
	v_mfma_f32_16x16x32_bf16 v[120:123], v[136:139], v[172:175], v[120:123]
	v_mfma_f32_16x16x32_bf16 v[116:119], v[104:107], v[190:193], v[116:119]
	v_mfma_f32_16x16x32_bf16 v[112:115], v[136:139], v[190:193], v[112:115]
	v_mfma_f32_16x16x32_bf16 v[100:103], v[104:107], v[198:201], v[100:103]
	v_mfma_f32_16x16x32_bf16 v[96:99], v[136:139], v[198:201], v[96:99]
	v_mfma_f32_16x16x32_bf16 v[132:135], v[108:111], v[168:171], v[132:135]
	v_mfma_f32_16x16x32_bf16 v[128:131], v[140:143], v[168:171], v[128:131]
	v_mfma_f32_16x16x32_bf16 v[124:127], v[108:111], v[186:189], v[124:127]
	v_mfma_f32_16x16x32_bf16 v[120:123], v[140:143], v[186:189], v[120:123]
	v_mfma_f32_16x16x32_bf16 v[116:119], v[108:111], v[194:197], v[116:119]
	v_mfma_f32_16x16x32_bf16 v[112:115], v[140:143], v[194:197], v[112:115]
	v_mfma_f32_16x16x32_bf16 v[100:103], v[108:111], v[202:205], v[100:103]
	v_mfma_f32_16x16x32_bf16 v[96:99], v[140:143], v[202:205], v[96:99]
	s_setprio 0
	s_setprio 1
	v_mfma_f32_16x16x32_bf16 v[60:63], v[148:151], v[164:167], v[60:63]
	v_mfma_f32_16x16x32_bf16 v[56:59], v[156:159], v[164:167], v[56:59]
	v_mfma_f32_16x16x32_bf16 v[52:55], v[148:151], v[172:175], v[52:55]
	v_mfma_f32_16x16x32_bf16 v[48:51], v[156:159], v[172:175], v[48:51]
	v_mfma_f32_16x16x32_bf16 v[44:47], v[148:151], v[190:193], v[44:47]
	v_mfma_f32_16x16x32_bf16 v[40:43], v[156:159], v[190:193], v[40:43]
	v_mfma_f32_16x16x32_bf16 v[36:39], v[148:151], v[198:201], v[36:39]
	v_mfma_f32_16x16x32_bf16 v[32:35], v[156:159], v[198:201], v[32:35]
	v_mfma_f32_16x16x32_bf16 v[60:63], v[152:155], v[168:171], v[60:63]
	v_mfma_f32_16x16x32_bf16 v[56:59], v[160:163], v[168:171], v[56:59]
	v_mfma_f32_16x16x32_bf16 v[52:55], v[152:155], v[186:189], v[52:55]
	v_mfma_f32_16x16x32_bf16 v[48:51], v[160:163], v[186:189], v[48:51]
	v_mfma_f32_16x16x32_bf16 v[44:47], v[152:155], v[194:197], v[44:47]
	v_mfma_f32_16x16x32_bf16 v[40:43], v[160:163], v[194:197], v[40:43]
	v_mfma_f32_16x16x32_bf16 v[36:39], v[152:155], v[202:205], v[36:39]
	v_mfma_f32_16x16x32_bf16 v[32:35], v[160:163], v[202:205], v[32:35]
	s_setprio 0
	s_barrier
	s_and_b32 s37, s18, 0xffff
	s_mov_b32 m0, s75
	s_mov_b32 s38, s6
	s_mov_b32 s39, s7
	s_add_u32 s4, s36, 0x4000
	ds_read_b128 v[164:167], v182 offset:16384
	ds_read_b128 v[168:171], v182 offset:17408
	ds_read_b128 v[172:175], v182 offset:18432
	ds_read_b128 v[186:189], v182 offset:19456
	ds_read_b128 v[190:193], v182 offset:20480
	ds_read_b128 v[194:197], v182 offset:21504
	ds_read_b128 v[198:201], v182 offset:22528
	ds_read_b128 v[202:205], v182 offset:23552
	buffer_load_dwordx4 v177, s[36:39], 0 offen lds
	s_mov_b32 m0, s77
	s_addc_u32 s5, s18, 0
	buffer_load_dwordx4 v179, s[36:39], 0 offen lds
	s_and_b32 s5, s5, 0xffff
	s_mov_b32 m0, s78
	s_and_b32 s41, s19, 0xffff
	buffer_load_dwordx4 v177, s[4:7], 0 offen lds
	s_mov_b32 m0, s79
	s_mov_b32 s42, s6
	buffer_load_dwordx4 v179, s[4:7], 0 offen lds
	s_mov_b32 s43, s7
	s_mov_b32 m0, s74
	s_nop 0
	buffer_load_dwordx4 v176, s[40:43], 0 offen lds
	s_mov_b32 m0, s80
	s_nop 0
	buffer_load_dwordx4 v178, s[40:43], 0 offen lds
	s_waitcnt vmcnt(8)
	s_waitcnt lgkmcnt(0)
	s_barrier
; #define PG8_STAGE(bufoff, gbase, voff) do { const __amdgpu_buffer_rsrc_t _rs = __builtin_amdgcn_make_buffer_rsrc((void*)(gbase), 0, 0x7fffffff, 0x00020000); _Pragma("unroll") for (int _i = 0; _i < 2; ++_i) \
;         __builtin_amdgcn_raw_ptr_buffer_load_lds(_rs, (LAS unsigned*)(lds + (bufoff) + ldsw + _i * 8192), 16, (int)(voff)[_i], 0, 0, 0); } while (0)
; #define PG8_WAIT_V(n) asm volatile("s_waitcnt vmcnt(" #n ")" ::: "memory")
; #define PG8_WAIT_L(n) asm volatile("s_waitcnt lgkmcnt(" #n ")" ::: "memory")
; #define PG8_BAR __builtin_amdgcn_s_barrier()
; #define PG8_SCHED __builtin_amdgcn_sched_barrier(0)
; template <class Epi, class Sched, bool F8 = false>
; __device__ __forceinline__ void gemm_phase(LAS unsigned char* lds, const int lda, const int ldb, const Sched& S, const Epi& E) {
;     ...
;             PG8_WAIT_V(8); PG8_WAIT_L(0); PG8_BAR; PG8_MMA(1, 0, At, B0); PG8_MMA(1, 1, At, B1); PG8_BAR; PG8_SCHED;
;             PG8_LDB(B0, 1, 0); PG8_LDB(B1, 1, 1); PG8_SCHED; PG8_LDA(At, 1, 0); PG8_STAGE(PG8_SA(0, 1), a2 + hstepA, voffA);
;             PG8_WAIT_V(8); PG8_WAIT_L(0); PG8_BAR; PG8_MMA(0, 0, At, B0); PG8_MMA(0, 1, At, B1); PG8_BAR; PG8_SCHED;
	s_setprio 1
	v_mfma_f32_16x16x32_bf16 v[92:95], v[104:107], v[164:167], v[92:95]
	v_mfma_f32_16x16x32_bf16 v[88:91], v[136:139], v[164:167], v[88:91]
	v_mfma_f32_16x16x32_bf16 v[84:87], v[104:107], v[172:175], v[84:87]
	v_mfma_f32_16x16x32_bf16 v[80:83], v[136:139], v[172:175], v[80:83]
	v_mfma_f32_16x16x32_bf16 v[76:79], v[104:107], v[190:193], v[76:79]
	v_mfma_f32_16x16x32_bf16 v[72:75], v[136:139], v[190:193], v[72:75]
	v_mfma_f32_16x16x32_bf16 v[68:71], v[104:107], v[198:201], v[68:71]
	v_mfma_f32_16x16x32_bf16 v[64:67], v[136:139], v[198:201], v[64:67]
	v_mfma_f32_16x16x32_bf16 v[92:95], v[108:111], v[168:171], v[92:95]
	v_mfma_f32_16x16x32_bf16 v[88:91], v[140:143], v[168:171], v[88:91]
	v_mfma_f32_16x16x32_bf16 v[84:87], v[108:111], v[186:189], v[84:87]
	v_mfma_f32_16x16x32_bf16 v[80:83], v[140:143], v[186:189], v[80:83]
	v_mfma_f32_16x16x32_bf16 v[76:79], v[108:111], v[194:197], v[76:79]
	v_mfma_f32_16x16x32_bf16 v[72:75], v[140:143], v[194:197], v[72:75]
	v_mfma_f32_16x16x32_bf16 v[68:71], v[108:111], v[202:205], v[68:71]
	v_mfma_f32_16x16x32_bf16 v[64:67], v[140:143], v[202:205], v[64:67]
	s_setprio 0
	s_setprio 1
	v_mfma_f32_16x16x32_bf16 v[28:31], v[148:151], v[164:167], v[28:31]
	v_mfma_f32_16x16x32_bf16 v[24:27], v[156:159], v[164:167], v[24:27]
	v_mfma_f32_16x16x32_bf16 v[20:23], v[148:151], v[172:175], v[20:23]
	v_mfma_f32_16x16x32_bf16 v[16:19], v[156:159], v[172:175], v[16:19]
	v_mfma_f32_16x16x32_bf16 v[12:15], v[148:151], v[190:193], v[12:15]
	v_mfma_f32_16x16x32_bf16 v[8:11], v[156:159], v[190:193], v[8:11]
	v_mfma_f32_16x16x32_bf16 v[4:7], v[148:151], v[198:201], v[4:7]
	v_mfma_f32_16x16x32_bf16 v[0:3], v[156:159], v[198:201], v[0:3]
	v_mfma_f32_16x16x32_bf16 v[28:31], v[152:155], v[168:171], v[28:31]
	v_mfma_f32_16x16x32_bf16 v[24:27], v[160:163], v[168:171], v[24:27]
	v_mfma_f32_16x16x32_bf16 v[20:23], v[152:155], v[186:189], v[20:23]
	v_mfma_f32_16x16x32_bf16 v[16:19], v[160:163], v[186:189], v[16:19]
	v_mfma_f32_16x16x32_bf16 v[12:15], v[152:155], v[194:197], v[12:15]
	v_mfma_f32_16x16x32_bf16 v[8:11], v[160:163], v[194:197], v[8:11]
	v_mfma_f32_16x16x32_bf16 v[4:7], v[152:155], v[202:205], v[4:7]
	v_mfma_f32_16x16x32_bf16 v[0:3], v[160:163], v[202:205], v[0:3]
	s_setprio 0
	s_barrier
	ds_read_b128 v[104:107], v183
	ds_read_b128 v[108:111], v183 offset:1024
	ds_read_b128 v[136:139], v183 offset:2048
	ds_read_b128 v[140:143], v183 offset:3072
	ds_read_b128 v[148:151], v184
	ds_read_b128 v[152:155], v184 offset:1024
	ds_read_b128 v[156:159], v184 offset:2048
	ds_read_b128 v[160:163], v184 offset:3072
	s_add_u32 s4, s40, 0x80000
	s_addc_u32 s5, s19, 0
	s_and_b32 s5, s5, 0xffff
	s_mov_b32 m0, s81
	ds_read_b128 v[164:167], v182 offset:32768
	ds_read_b128 v[168:171], v182 offset:33792
	ds_read_b128 v[172:175], v182 offset:34816
	ds_read_b128 v[186:189], v182 offset:35840
	ds_read_b128 v[190:193], v182 offset:36864
	ds_read_b128 v[194:197], v182 offset:37888
	ds_read_b128 v[198:201], v182 offset:38912
	ds_read_b128 v[202:205], v182 offset:39936
	buffer_load_dwordx4 v176, s[4:7], 0 offen lds
	s_mov_b32 m0, s82
	s_nop 0
	buffer_load_dwordx4 v178, s[4:7], 0 offen lds
	s_waitcnt vmcnt(8)
	s_waitcnt lgkmcnt(0)
	s_barrier
	s_setprio 1
	v_mfma_f32_16x16x32_bf16 v[132:135], v[104:107], v[164:167], v[132:135]
	v_mfma_f32_16x16x32_bf16 v[128:131], v[136:139], v[164:167], v[128:131]
	v_mfma_f32_16x16x32_bf16 v[124:127], v[104:107], v[172:175], v[124:127]
	v_mfma_f32_16x16x32_bf16 v[120:123], v[136:139], v[172:175], v[120:123]
	v_mfma_f32_16x16x32_bf16 v[116:119], v[104:107], v[190:193], v[116:119]
	v_mfma_f32_16x16x32_bf16 v[112:115], v[136:139], v[190:193], v[112:115]
	v_mfma_f32_16x16x32_bf16 v[100:103], v[104:107], v[198:201], v[100:103]
	v_mfma_f32_16x16x32_bf16 v[96:99], v[136:139], v[198:201], v[96:99]
	v_mfma_f32_16x16x32_bf16 v[132:135], v[108:111], v[168:171], v[132:135]
	v_mfma_f32_16x16x32_bf16 v[128:131], v[140:143], v[168:171], v[128:131]
	v_mfma_f32_16x16x32_bf16 v[124:127], v[108:111], v[186:189], v[124:127]
	v_mfma_f32_16x16x32_bf16 v[120:123], v[140:143], v[186:189], v[120:123]
	v_mfma_f32_16x16x32_bf16 v[116:119], v[108:111], v[194:197], v[116:119]
	v_mfma_f32_16x16x32_bf16 v[112:115], v[140:143], v[194:197], v[112:115]
	v_mfma_f32_16x16x32_bf16 v[100:103], v[108:111], v[202:205], v[100:103]
	v_mfma_f32_16x16x32_bf16 v[96:99], v[140:143], v[202:205], v[96:99]
	s_setprio 0
	s_setprio 1
	v_mfma_f32_16x16x32_bf16 v[60:63], v[148:151], v[164:167], v[60:63]
	v_mfma_f32_16x16x32_bf16 v[56:59], v[156:159], v[164:167], v[56:59]
	v_mfma_f32_16x16x32_bf16 v[52:55], v[148:151], v[172:175], v[52:55]
	v_mfma_f32_16x16x32_bf16 v[48:51], v[156:159], v[172:175], v[48:51]
	v_mfma_f32_16x16x32_bf16 v[44:47], v[148:151], v[190:193], v[44:47]
	v_mfma_f32_16x16x32_bf16 v[40:43], v[156:159], v[190:193], v[40:43]
	v_mfma_f32_16x16x32_bf16 v[36:39], v[148:151], v[198:201], v[36:39]
	v_mfma_f32_16x16x32_bf16 v[32:35], v[156:159], v[198:201], v[32:35]
	v_mfma_f32_16x16x32_bf16 v[60:63], v[152:155], v[168:171], v[60:63]
	v_mfma_f32_16x16x32_bf16 v[56:59], v[160:163], v[168:171], v[56:59]
	v_mfma_f32_16x16x32_bf16 v[52:55], v[152:155], v[186:189], v[52:55]
	v_mfma_f32_16x16x32_bf16 v[48:51], v[160:163], v[186:189], v[48:51]
	v_mfma_f32_16x16x32_bf16 v[44:47], v[152:155], v[194:197], v[44:47]
	v_mfma_f32_16x16x32_bf16 v[40:43], v[160:163], v[194:197], v[40:43]
	v_mfma_f32_16x16x32_bf16 v[36:39], v[152:155], v[202:205], v[36:39]
	v_mfma_f32_16x16x32_bf16 v[32:35], v[160:163], v[202:205], v[32:35]
	s_setprio 0
	s_barrier
; #define PG8_STAGE(bufoff, gbase, voff) do { const __amdgpu_buffer_rsrc_t _rs = __builtin_amdgcn_make_buffer_rsrc((void*)(gbase), 0, 0x7fffffff, 0x00020000); _Pragma("unroll") for (int _i = 0; _i < 2; ++_i) \
;         __builtin_amdgcn_raw_ptr_buffer_load_lds(_rs, (LAS unsigned*)(lds + (bufoff) + ldsw + _i * 8192), 16, (int)(voff)[_i], 0, 0, 0); } while (0)
; #define PG8_WAIT_V(n) asm volatile("s_waitcnt vmcnt(" #n ")" ::: "memory")
; #define PG8_WAIT_L(n) asm volatile("s_waitcnt lgkmcnt(" #n ")" ::: "memory")
; #define PG8_BAR __builtin_amdgcn_s_barrier()
; #define PG8_SCHED __builtin_amdgcn_sched_barrier(0)
; template <class Epi, class Sched, bool F8 = false>
; __device__ __forceinline__ void gemm_phase(LAS unsigned char* lds, const int lda, const int ldb, const Sched& S, const Epi& E) {
;     ...
;             PG8_LDA(At, 1, 1); PG8_STAGE(PG8_SB(1, 0), b3, voffB); PG8_STAGE(PG8_SB(1, 1), b3 + hstepB, voffB); PG8_STAGE(PG8_SA(1, 0), a3, voffA);
;             PG8_WAIT_V(8); PG8_WAIT_L(0); PG8_BAR; PG8_MMA(1, 0, At, B0); PG8_MMA(1, 1, At, B1); PG8_BAR; PG8_SCHED;
	s_add_u32 s4, s36, 0x8000
	s_addc_u32 s5, s18, 0
	s_mov_b32 m0, s86
	s_and_b32 s5, s5, 0xffff
	ds_read_b128 v[164:167], v182 offset:49152
	ds_read_b128 v[168:171], v182 offset:50176
	ds_read_b128 v[172:175], v182 offset:51200
	ds_read_b128 v[186:189], v182 offset:52224
	ds_read_b128 v[190:193], v182 offset:53248
	ds_read_b128 v[194:197], v182 offset:54272
	ds_read_b128 v[198:201], v182 offset:55296
	ds_read_b128 v[202:205], v182 offset:56320
	buffer_load_dwordx4 v177, s[4:7], 0 offen lds
	s_mov_b32 m0, s87
	s_mov_b32 s19, s7
	buffer_load_dwordx4 v179, s[4:7], 0 offen lds
	s_add_u32 s4, s36, 0xc000
	s_addc_u32 s5, s18, 0
	s_and_b32 s5, s5, 0xffff
	s_mov_b32 m0, s90
	s_and_b32 s17, s17, 0xffff
	buffer_load_dwordx4 v177, s[4:7], 0 offen lds
	s_mov_b32 m0, s91
	s_mov_b32 s18, s6
	buffer_load_dwordx4 v179, s[4:7], 0 offen lds
	s_mov_b32 m0, s88
	s_nop 0
	buffer_load_dwordx4 v176, s[16:19], 0 offen lds
	s_mov_b32 m0, s89
	s_nop 0
	buffer_load_dwordx4 v178, s[16:19], 0 offen lds
	s_waitcnt vmcnt(8)
	s_waitcnt lgkmcnt(0)
	s_barrier
	s_setprio 1
	v_mfma_f32_16x16x32_bf16 v[92:95], v[104:107], v[164:167], v[92:95]
	v_mfma_f32_16x16x32_bf16 v[88:91], v[136:139], v[164:167], v[88:91]
	v_mfma_f32_16x16x32_bf16 v[84:87], v[104:107], v[172:175], v[84:87]
	v_mfma_f32_16x16x32_bf16 v[80:83], v[136:139], v[172:175], v[80:83]
	v_mfma_f32_16x16x32_bf16 v[76:79], v[104:107], v[190:193], v[76:79]
	v_mfma_f32_16x16x32_bf16 v[72:75], v[136:139], v[190:193], v[72:75]
	v_mfma_f32_16x16x32_bf16 v[68:71], v[104:107], v[198:201], v[68:71]
	v_mfma_f32_16x16x32_bf16 v[64:67], v[136:139], v[198:201], v[64:67]
	v_mfma_f32_16x16x32_bf16 v[92:95], v[108:111], v[168:171], v[92:95]
	v_mfma_f32_16x16x32_bf16 v[88:91], v[140:143], v[168:171], v[88:91]
	v_mfma_f32_16x16x32_bf16 v[84:87], v[108:111], v[186:189], v[84:87]
	v_mfma_f32_16x16x32_bf16 v[80:83], v[140:143], v[186:189], v[80:83]
	v_mfma_f32_16x16x32_bf16 v[76:79], v[108:111], v[194:197], v[76:79]
	v_mfma_f32_16x16x32_bf16 v[72:75], v[140:143], v[194:197], v[72:75]
	v_mfma_f32_16x16x32_bf16 v[68:71], v[108:111], v[202:205], v[68:71]
	v_mfma_f32_16x16x32_bf16 v[64:67], v[140:143], v[202:205], v[64:67]
	s_setprio 0
	s_setprio 1
	v_mfma_f32_16x16x32_bf16 v[28:31], v[148:151], v[164:167], v[28:31]
	v_mfma_f32_16x16x32_bf16 v[24:27], v[156:159], v[164:167], v[24:27]
	v_mfma_f32_16x16x32_bf16 v[20:23], v[148:151], v[172:175], v[20:23]
	v_mfma_f32_16x16x32_bf16 v[16:19], v[156:159], v[172:175], v[16:19]
	v_mfma_f32_16x16x32_bf16 v[12:15], v[148:151], v[190:193], v[12:15]
	v_mfma_f32_16x16x32_bf16 v[8:11], v[156:159], v[190:193], v[8:11]
	v_mfma_f32_16x16x32_bf16 v[4:7], v[148:151], v[198:201], v[4:7]
	v_mfma_f32_16x16x32_bf16 v[0:3], v[156:159], v[198:201], v[0:3]
	v_mfma_f32_16x16x32_bf16 v[28:31], v[152:155], v[168:171], v[28:31]
	v_mfma_f32_16x16x32_bf16 v[24:27], v[160:163], v[168:171], v[24:27]
	v_mfma_f32_16x16x32_bf16 v[20:23], v[152:155], v[186:189], v[20:23]
	v_mfma_f32_16x16x32_bf16 v[16:19], v[160:163], v[186:189], v[16:19]
	v_mfma_f32_16x16x32_bf16 v[12:15], v[152:155], v[194:197], v[12:15]
	v_mfma_f32_16x16x32_bf16 v[8:11], v[160:163], v[194:197], v[8:11]
	v_mfma_f32_16x16x32_bf16 v[4:7], v[152:155], v[202:205], v[4:7]
	v_mfma_f32_16x16x32_bf16 v[0:3], v[160:163], v[202:205], v[0:3]
	s_setprio 0
	s_barrier
	s_add_u32 s63, s63, 0x10000
	s_addc_u32 vcc_lo, vcc_lo, 0
	s_add_u32 vcc_hi, vcc_hi, 0x100
	s_addc_u32 s35, s35, 0
	s_cmp_ge_i32 s64, s9
	s_mov_b32 s4, s64
	s_cbranch_scc0 .LBB0_408
	s_and_b64 vcc, exec, s[66:67]
	s_cbranch_vccz .LBB0_411
	s_barrier

; #define PG8_STAGE(bufoff, gbase, voff) do { const __amdgpu_buffer_rsrc_t _rs = __builtin_amdgcn_make_buffer_rsrc((void*)(gbase), 0, 0x7fffffff, 0x00020000); _Pragma("unroll") for (int _i = 0; _i < 2; ++_i) \
;         __builtin_amdgcn_raw_ptr_buffer_load_lds(_rs, (LAS unsigned*)(lds + (bufoff) + ldsw + _i * 8192), 16, (int)(voff)[_i], 0, 0, 0); } while (0)
; #define PG8_WAIT_V(n) asm volatile("s_waitcnt vmcnt(" #n ")" ::: "memory")
; #define PG8_WAIT_L(n) asm volatile("s_waitcnt lgkmcnt(" #n ")" ::: "memory")
; #define PG8_BAR __builtin_amdgcn_s_barrier()
; #define PG8_SCHED __builtin_amdgcn_sched_barrier(0)
; template <class Epi, class Sched, bool F8 = false>
; __device__ __forceinline__ void gemm_phase(LAS unsigned char* lds, const int lda, const int ldb, const Sched& S, const Epi& E) {
;     ...
;             const bool last = (t == nt - 2);
;             const char* a1 = cA + (size_t)(t + 1) * kstep;
;             const char* a2 = last ? nA : cA + (size_t)(t + 2) * kstep; const char* b2 = last ? nB : cB + (size_t)(t + 2) * kstepB;
;             const char* a3 = a2 + kstep; const char* b3 = b2 + kstepB;
;     ...
;             PG8_LDB(B0, 0, 0); PG8_LDB(B1, 0, 1); PG8_SCHED; PG8_LDA(At, 0, 0); PG8_STAGE(PG8_SA(1, 1), a1 + hstepA, voffA);
;             PG8_WAIT_V(8); PG8_WAIT_L(0); PG8_BAR; PG8_MMA(0, 0, At, B0); PG8_MMA(0, 1, At, B1); PG8_BAR; PG8_SCHED;
;             PG8_LDA(At, 0, 1); PG8_STAGE(PG8_SB(0, 0), b2, voffB); PG8_STAGE(PG8_SB(0, 1), b2 + hstepB, voffB); PG8_STAGE(PG8_SA(0, 0), a2, voffA);
;             PG8_WAIT_V(8); PG8_WAIT_L(0); PG8_BAR; PG8_MMA(1, 0, At, B0); PG8_MMA(1, 1, At, B1); PG8_BAR; PG8_SCHED;
.LBB0_485:
	v_add_u32_e32 v144, 0x10000, v152
	v_add_u32_e32 v166, 0x14000, v152
	ds_read_b128 v[132:135], v144
	ds_read_b128 v[136:139], v144 offset:1024
	ds_read_b128 v[140:143], v144 offset:2048
	ds_read_b128 v[144:147], v144 offset:3072
	ds_read_b128 v[154:157], v166
	ds_read_b128 v[158:161], v166 offset:1024
	ds_read_b128 v[162:165], v166 offset:2048
	ds_read_b128 v[166:169], v166 offset:3072
	s_add_u32 s4, s47, 0xfff80080
	s_addc_u32 s5, s62, -1
	s_cmp_eq_u32 s63, 28
	s_cselect_b32 s40, s48, s4
	s_cselect_b32 s19, s49, s5
	s_cselect_b32 s18, s51, s33
	s_cselect_b32 s36, s50, s9
	s_add_u32 s16, s40, 0x80
	s_addc_u32 s17, s19, 0
	s_and_b32 s5, s62, 0xffff
	s_mov_b32 s4, s47
	s_mov_b32 m0, s91
	ds_read_b128 v[170:173], v153
	ds_read_b128 v[174:177], v153 offset:1024
	ds_read_b128 v[178:181], v153 offset:2048
	ds_read_b128 v[182:185], v153 offset:3072
	ds_read_b128 v[186:189], v153 offset:4096
	ds_read_b128 v[190:193], v153 offset:5120
	ds_read_b128 v[194:197], v153 offset:6144
	ds_read_b128 v[198:201], v153 offset:7168
	buffer_load_dwordx4 v148, s[4:7], 0 offen lds
	s_mov_b32 m0, s92
	s_nop 0
	buffer_load_dwordx4 v150, s[4:7], 0 offen lds
	s_waitcnt vmcnt(8)
	s_waitcnt lgkmcnt(0)
	s_barrier
	s_setprio 1
	v_mfma_f32_16x16x32_bf16 v[124:127], v[132:135], v[170:173], v[124:127]
	v_mfma_f32_16x16x32_bf16 v[120:123], v[140:143], v[170:173], v[120:123]
	v_mfma_f32_16x16x32_bf16 v[116:119], v[132:135], v[178:181], v[116:119]
	v_mfma_f32_16x16x32_bf16 v[112:115], v[140:143], v[178:181], v[112:115]
	v_mfma_f32_16x16x32_bf16 v[108:111], v[132:135], v[186:189], v[108:111]
	v_mfma_f32_16x16x32_bf16 v[104:107], v[140:143], v[186:189], v[104:107]
	v_mfma_f32_16x16x32_bf16 v[100:103], v[132:135], v[194:197], v[100:103]
	v_mfma_f32_16x16x32_bf16 v[96:99], v[140:143], v[194:197], v[96:99]
	v_mfma_f32_16x16x32_bf16 v[124:127], v[136:139], v[174:177], v[124:127]
	v_mfma_f32_16x16x32_bf16 v[120:123], v[144:147], v[174:177], v[120:123]
	v_mfma_f32_16x16x32_bf16 v[116:119], v[136:139], v[182:185], v[116:119]
	v_mfma_f32_16x16x32_bf16 v[112:115], v[144:147], v[182:185], v[112:115]
	v_mfma_f32_16x16x32_bf16 v[108:111], v[136:139], v[190:193], v[108:111]
	v_mfma_f32_16x16x32_bf16 v[104:107], v[144:147], v[190:193], v[104:107]
	v_mfma_f32_16x16x32_bf16 v[100:103], v[136:139], v[198:201], v[100:103]
	v_mfma_f32_16x16x32_bf16 v[96:99], v[144:147], v[198:201], v[96:99]
	s_setprio 0
	s_setprio 1
	v_mfma_f32_16x16x32_bf16 v[92:95], v[154:157], v[170:173], v[92:95]
	v_mfma_f32_16x16x32_bf16 v[88:91], v[162:165], v[170:173], v[88:91]
	v_mfma_f32_16x16x32_bf16 v[84:87], v[154:157], v[178:181], v[84:87]
	v_mfma_f32_16x16x32_bf16 v[80:83], v[162:165], v[178:181], v[80:83]
	v_mfma_f32_16x16x32_bf16 v[76:79], v[154:157], v[186:189], v[76:79]
	v_mfma_f32_16x16x32_bf16 v[72:75], v[162:165], v[186:189], v[72:75]
	v_mfma_f32_16x16x32_bf16 v[68:71], v[154:157], v[194:197], v[68:71]
	v_mfma_f32_16x16x32_bf16 v[64:67], v[162:165], v[194:197], v[64:67]
	v_mfma_f32_16x16x32_bf16 v[92:95], v[158:161], v[174:177], v[92:95]
	v_mfma_f32_16x16x32_bf16 v[88:91], v[166:169], v[174:177], v[88:91]
	v_mfma_f32_16x16x32_bf16 v[84:87], v[158:161], v[182:185], v[84:87]
	v_mfma_f32_16x16x32_bf16 v[80:83], v[166:169], v[182:185], v[80:83]
	v_mfma_f32_16x16x32_bf16 v[76:79], v[158:161], v[190:193], v[76:79]
	v_mfma_f32_16x16x32_bf16 v[72:75], v[166:169], v[190:193], v[72:75]
	v_mfma_f32_16x16x32_bf16 v[68:71], v[158:161], v[198:201], v[68:71]
	v_mfma_f32_16x16x32_bf16 v[64:67], v[166:169], v[198:201], v[64:67]
	s_setprio 0
	s_barrier
	s_and_b32 s37, s18, 0xffff
	s_mov_b32 m0, s70
	s_mov_b32 s38, s6
	s_mov_b32 s39, s7
	s_add_u32 s4, s36, 0x4000
	ds_read_b128 v[170:173], v153 offset:16384
	ds_read_b128 v[174:177], v153 offset:17408
	ds_read_b128 v[178:181], v153 offset:18432
	ds_read_b128 v[182:185], v153 offset:19456
	ds_read_b128 v[186:189], v153 offset:20480
	ds_read_b128 v[190:193], v153 offset:21504
	ds_read_b128 v[194:197], v153 offset:22528
	ds_read_b128 v[198:201], v153 offset:23552
	buffer_load_dwordx4 v149, s[36:39], 0 offen lds
	s_mov_b32 m0, s71
	s_addc_u32 s5, s18, 0
	buffer_load_dwordx4 v151, s[36:39], 0 offen lds
	s_and_b32 s5, s5, 0xffff
	s_mov_b32 m0, s72
	s_and_b32 s41, s19, 0xffff
	buffer_load_dwordx4 v149, s[4:7], 0 offen lds
	s_mov_b32 m0, s73
	s_mov_b32 s42, s6
	buffer_load_dwordx4 v151, s[4:7], 0 offen lds
	s_mov_b32 s43, s7
	s_mov_b32 m0, s67
	s_nop 0
	buffer_load_dwordx4 v148, s[40:43], 0 offen lds
	s_mov_b32 m0, s74
	s_nop 0
	buffer_load_dwordx4 v150, s[40:43], 0 offen lds
	s_waitcnt vmcnt(8)
	s_waitcnt lgkmcnt(0)
	s_barrier
; #define PG8_STAGE(bufoff, gbase, voff) do { const __amdgpu_buffer_rsrc_t _rs = __builtin_amdgcn_make_buffer_rsrc((void*)(gbase), 0, 0x7fffffff, 0x00020000); _Pragma("unroll") for (int _i = 0; _i < 2; ++_i) \
;         __builtin_amdgcn_raw_ptr_buffer_load_lds(_rs, (LAS unsigned*)(lds + (bufoff) + ldsw + _i * 8192), 16, (int)(voff)[_i], 0, 0, 0); } while (0)
; #define PG8_WAIT_V(n) asm volatile("s_waitcnt vmcnt(" #n ")" ::: "memory")
; #define PG8_WAIT_L(n) asm volatile("s_waitcnt lgkmcnt(" #n ")" ::: "memory")
; #define PG8_BAR __builtin_amdgcn_s_barrier()
; #define PG8_SCHED __builtin_amdgcn_sched_barrier(0)
; template <class Epi, class Sched, bool F8 = false>
; __device__ __forceinline__ void gemm_phase(LAS unsigned char* lds, const int lda, const int ldb, const Sched& S, const Epi& E) {
;     ...
;             PG8_WAIT_V(8); PG8_WAIT_L(0); PG8_BAR; PG8_MMA(1, 0, At, B0); PG8_MMA(1, 1, At, B1); PG8_BAR; PG8_SCHED;
;             PG8_LDB(B0, 1, 0); PG8_LDB(B1, 1, 1); PG8_SCHED; PG8_LDA(At, 1, 0); PG8_STAGE(PG8_SA(0, 1), a2 + hstepA, voffA);
;             PG8_WAIT_V(8); PG8_WAIT_L(0); PG8_BAR; PG8_MMA(0, 0, At, B0); PG8_MMA(0, 1, At, B1); PG8_BAR; PG8_SCHED;
	s_setprio 1
	v_mfma_f32_16x16x32_bf16 v[60:63], v[132:135], v[170:173], v[60:63]
	v_mfma_f32_16x16x32_bf16 v[56:59], v[140:143], v[170:173], v[56:59]
	v_mfma_f32_16x16x32_bf16 v[52:55], v[132:135], v[178:181], v[52:55]
	v_mfma_f32_16x16x32_bf16 v[48:51], v[140:143], v[178:181], v[48:51]
	v_mfma_f32_16x16x32_bf16 v[44:47], v[132:135], v[186:189], v[44:47]
	v_mfma_f32_16x16x32_bf16 v[40:43], v[140:143], v[186:189], v[40:43]
	v_mfma_f32_16x16x32_bf16 v[36:39], v[132:135], v[194:197], v[36:39]
	v_mfma_f32_16x16x32_bf16 v[32:35], v[140:143], v[194:197], v[32:35]
	v_mfma_f32_16x16x32_bf16 v[60:63], v[136:139], v[174:177], v[60:63]
	v_mfma_f32_16x16x32_bf16 v[56:59], v[144:147], v[174:177], v[56:59]
	v_mfma_f32_16x16x32_bf16 v[52:55], v[136:139], v[182:185], v[52:55]
	v_mfma_f32_16x16x32_bf16 v[48:51], v[144:147], v[182:185], v[48:51]
	v_mfma_f32_16x16x32_bf16 v[44:47], v[136:139], v[190:193], v[44:47]
	v_mfma_f32_16x16x32_bf16 v[40:43], v[144:147], v[190:193], v[40:43]
	v_mfma_f32_16x16x32_bf16 v[36:39], v[136:139], v[198:201], v[36:39]
	v_mfma_f32_16x16x32_bf16 v[32:35], v[144:147], v[198:201], v[32:35]
	s_setprio 0
	s_setprio 1
	v_mfma_f32_16x16x32_bf16 v[28:31], v[154:157], v[170:173], v[28:31]
	v_mfma_f32_16x16x32_bf16 v[24:27], v[162:165], v[170:173], v[24:27]
	v_mfma_f32_16x16x32_bf16 v[20:23], v[154:157], v[178:181], v[20:23]
	v_mfma_f32_16x16x32_bf16 v[16:19], v[162:165], v[178:181], v[16:19]
	v_mfma_f32_16x16x32_bf16 v[12:15], v[154:157], v[186:189], v[12:15]
	v_mfma_f32_16x16x32_bf16 v[8:11], v[162:165], v[186:189], v[8:11]
	v_mfma_f32_16x16x32_bf16 v[4:7], v[154:157], v[194:197], v[4:7]
	v_mfma_f32_16x16x32_bf16 v[0:3], v[162:165], v[194:197], v[0:3]
	v_mfma_f32_16x16x32_bf16 v[28:31], v[158:161], v[174:177], v[28:31]
	v_mfma_f32_16x16x32_bf16 v[24:27], v[166:169], v[174:177], v[24:27]
	v_mfma_f32_16x16x32_bf16 v[20:23], v[158:161], v[182:185], v[20:23]
	v_mfma_f32_16x16x32_bf16 v[16:19], v[166:169], v[182:185], v[16:19]
	v_mfma_f32_16x16x32_bf16 v[12:15], v[158:161], v[190:193], v[12:15]
	v_mfma_f32_16x16x32_bf16 v[8:11], v[166:169], v[190:193], v[8:11]
	v_mfma_f32_16x16x32_bf16 v[4:7], v[158:161], v[198:201], v[4:7]
	v_mfma_f32_16x16x32_bf16 v[0:3], v[166:169], v[198:201], v[0:3]
	s_setprio 0
	s_barrier
	v_add_u32_e32 v144, 0x18000, v152
	v_add_u32_e32 v166, 0x1c000, v152
	ds_read_b128 v[132:135], v144
	ds_read_b128 v[136:139], v144 offset:1024
	ds_read_b128 v[140:143], v144 offset:2048
	ds_read_b128 v[144:147], v144 offset:3072
	ds_read_b128 v[154:157], v166
	ds_read_b128 v[158:161], v166 offset:1024
	ds_read_b128 v[162:165], v166 offset:2048
	ds_read_b128 v[166:169], v166 offset:3072
	s_add_u32 s4, s40, 0x80000
	s_addc_u32 s5, s19, 0
	s_and_b32 s5, s5, 0xffff
	s_mov_b32 m0, s75
	ds_read_b128 v[170:173], v153 offset:32768
	ds_read_b128 v[174:177], v153 offset:33792
	ds_read_b128 v[178:181], v153 offset:34816
	ds_read_b128 v[182:185], v153 offset:35840
	ds_read_b128 v[186:189], v153 offset:36864
	ds_read_b128 v[190:193], v153 offset:37888
	ds_read_b128 v[194:197], v153 offset:38912
	ds_read_b128 v[198:201], v153 offset:39936
	buffer_load_dwordx4 v148, s[4:7], 0 offen lds
	s_mov_b32 m0, s76
	s_nop 0
	buffer_load_dwordx4 v150, s[4:7], 0 offen lds
	s_waitcnt vmcnt(8)
	s_waitcnt lgkmcnt(0)
	s_barrier
	s_setprio 1
	v_mfma_f32_16x16x32_bf16 v[124:127], v[132:135], v[170:173], v[124:127]
	v_mfma_f32_16x16x32_bf16 v[120:123], v[140:143], v[170:173], v[120:123]
	v_mfma_f32_16x16x32_bf16 v[116:119], v[132:135], v[178:181], v[116:119]
	v_mfma_f32_16x16x32_bf16 v[112:115], v[140:143], v[178:181], v[112:115]
	v_mfma_f32_16x16x32_bf16 v[108:111], v[132:135], v[186:189], v[108:111]
	v_mfma_f32_16x16x32_bf16 v[104:107], v[140:143], v[186:189], v[104:107]
	v_mfma_f32_16x16x32_bf16 v[100:103], v[132:135], v[194:197], v[100:103]
	v_mfma_f32_16x16x32_bf16 v[96:99], v[140:143], v[194:197], v[96:99]
	v_mfma_f32_16x16x32_bf16 v[124:127], v[136:139], v[174:177], v[124:127]
	v_mfma_f32_16x16x32_bf16 v[120:123], v[144:147], v[174:177], v[120:123]
	v_mfma_f32_16x16x32_bf16 v[116:119], v[136:139], v[182:185], v[116:119]
	v_mfma_f32_16x16x32_bf16 v[112:115], v[144:147], v[182:185], v[112:115]
	v_mfma_f32_16x16x32_bf16 v[108:111], v[136:139], v[190:193], v[108:111]
	v_mfma_f32_16x16x32_bf16 v[104:107], v[144:147], v[190:193], v[104:107]
	v_mfma_f32_16x16x32_bf16 v[100:103], v[136:139], v[198:201], v[100:103]
	v_mfma_f32_16x16x32_bf16 v[96:99], v[144:147], v[198:201], v[96:99]
	s_setprio 0
	s_setprio 1
	v_mfma_f32_16x16x32_bf16 v[92:95], v[154:157], v[170:173], v[92:95]
	v_mfma_f32_16x16x32_bf16 v[88:91], v[162:165], v[170:173], v[88:91]
	v_mfma_f32_16x16x32_bf16 v[84:87], v[154:157], v[178:181], v[84:87]
	v_mfma_f32_16x16x32_bf16 v[80:83], v[162:165], v[178:181], v[80:83]
	v_mfma_f32_16x16x32_bf16 v[76:79], v[154:157], v[186:189], v[76:79]
	v_mfma_f32_16x16x32_bf16 v[72:75], v[162:165], v[186:189], v[72:75]
	v_mfma_f32_16x16x32_bf16 v[68:71], v[154:157], v[194:197], v[68:71]
	v_mfma_f32_16x16x32_bf16 v[64:67], v[162:165], v[194:197], v[64:67]
	v_mfma_f32_16x16x32_bf16 v[92:95], v[158:161], v[174:177], v[92:95]
	v_mfma_f32_16x16x32_bf16 v[88:91], v[166:169], v[174:177], v[88:91]
	v_mfma_f32_16x16x32_bf16 v[84:87], v[158:161], v[182:185], v[84:87]
	v_mfma_f32_16x16x32_bf16 v[80:83], v[166:169], v[182:185], v[80:83]
	v_mfma_f32_16x16x32_bf16 v[76:79], v[158:161], v[190:193], v[76:79]
	v_mfma_f32_16x16x32_bf16 v[72:75], v[166:169], v[190:193], v[72:75]
	v_mfma_f32_16x16x32_bf16 v[68:71], v[158:161], v[198:201], v[68:71]
	v_mfma_f32_16x16x32_bf16 v[64:67], v[166:169], v[198:201], v[64:67]
	s_setprio 0
	s_barrier
; #define PG8_STAGE(bufoff, gbase, voff) do { const __amdgpu_buffer_rsrc_t _rs = __builtin_amdgcn_make_buffer_rsrc((void*)(gbase), 0, 0x7fffffff, 0x00020000); _Pragma("unroll") for (int _i = 0; _i < 2; ++_i) \
;         __builtin_amdgcn_raw_ptr_buffer_load_lds(_rs, (LAS unsigned*)(lds + (bufoff) + ldsw + _i * 8192), 16, (int)(voff)[_i], 0, 0, 0); } while (0)
; #define PG8_WAIT_V(n) asm volatile("s_waitcnt vmcnt(" #n ")" ::: "memory")
; #define PG8_WAIT_L(n) asm volatile("s_waitcnt lgkmcnt(" #n ")" ::: "memory")
; #define PG8_BAR __builtin_amdgcn_s_barrier()
; #define PG8_SCHED __builtin_amdgcn_sched_barrier(0)
; template <class Epi, class Sched, bool F8 = false>
; __device__ __forceinline__ void gemm_phase(LAS unsigned char* lds, const int lda, const int ldb, const Sched& S, const Epi& E) {
;     ...
;             PG8_LDA(At, 1, 1); PG8_STAGE(PG8_SB(1, 0), b3, voffB); PG8_STAGE(PG8_SB(1, 1), b3 + hstepB, voffB); PG8_STAGE(PG8_SA(1, 0), a3, voffA);
;             PG8_WAIT_V(8); PG8_WAIT_L(0); PG8_BAR; PG8_MMA(1, 0, At, B0); PG8_MMA(1, 1, At, B1); PG8_BAR; PG8_SCHED;
	s_add_u32 s4, s36, 0x8000
	s_addc_u32 s5, s18, 0
	s_mov_b32 m0, s85
	s_and_b32 s5, s5, 0xffff
	ds_read_b128 v[170:173], v153 offset:49152
	ds_read_b128 v[174:177], v153 offset:50176
	ds_read_b128 v[178:181], v153 offset:51200
	ds_read_b128 v[182:185], v153 offset:52224
	ds_read_b128 v[186:189], v153 offset:53248
	ds_read_b128 v[190:193], v153 offset:54272
	ds_read_b128 v[194:197], v153 offset:55296
	ds_read_b128 v[198:201], v153 offset:56320
	buffer_load_dwordx4 v149, s[4:7], 0 offen lds
	s_mov_b32 m0, s86
	s_mov_b32 s19, s7
	buffer_load_dwordx4 v151, s[4:7], 0 offen lds
	s_add_u32 s4, s36, 0xc000
	s_addc_u32 s5, s18, 0
	s_and_b32 s5, s5, 0xffff
	s_mov_b32 m0, s89
	s_and_b32 s17, s17, 0xffff
	buffer_load_dwordx4 v149, s[4:7], 0 offen lds
	s_mov_b32 m0, s90
	s_mov_b32 s18, s6
	buffer_load_dwordx4 v151, s[4:7], 0 offen lds
	s_mov_b32 m0, s87
	s_nop 0
	buffer_load_dwordx4 v148, s[16:19], 0 offen lds
	s_mov_b32 m0, s88
	s_nop 0
	buffer_load_dwordx4 v150, s[16:19], 0 offen lds
	s_waitcnt vmcnt(8)
	s_waitcnt lgkmcnt(0)
	s_barrier
	s_setprio 1
	v_mfma_f32_16x16x32_bf16 v[60:63], v[132:135], v[170:173], v[60:63]
	v_mfma_f32_16x16x32_bf16 v[56:59], v[140:143], v[170:173], v[56:59]
	v_mfma_f32_16x16x32_bf16 v[52:55], v[132:135], v[178:181], v[52:55]
	v_mfma_f32_16x16x32_bf16 v[48:51], v[140:143], v[178:181], v[48:51]
	v_mfma_f32_16x16x32_bf16 v[44:47], v[132:135], v[186:189], v[44:47]
	v_mfma_f32_16x16x32_bf16 v[40:43], v[140:143], v[186:189], v[40:43]
	v_mfma_f32_16x16x32_bf16 v[36:39], v[132:135], v[194:197], v[36:39]
	v_mfma_f32_16x16x32_bf16 v[32:35], v[140:143], v[194:197], v[32:35]
	v_mfma_f32_16x16x32_bf16 v[60:63], v[136:139], v[174:177], v[60:63]
	v_mfma_f32_16x16x32_bf16 v[56:59], v[144:147], v[174:177], v[56:59]
	v_mfma_f32_16x16x32_bf16 v[52:55], v[136:139], v[182:185], v[52:55]
	v_mfma_f32_16x16x32_bf16 v[48:51], v[144:147], v[182:185], v[48:51]
	v_mfma_f32_16x16x32_bf16 v[44:47], v[136:139], v[190:193], v[44:47]
	v_mfma_f32_16x16x32_bf16 v[40:43], v[144:147], v[190:193], v[40:43]
	v_mfma_f32_16x16x32_bf16 v[36:39], v[136:139], v[198:201], v[36:39]
	v_mfma_f32_16x16x32_bf16 v[32:35], v[144:147], v[198:201], v[32:35]
	s_setprio 0
	s_setprio 1
	v_mfma_f32_16x16x32_bf16 v[28:31], v[154:157], v[170:173], v[28:31]
	v_mfma_f32_16x16x32_bf16 v[24:27], v[162:165], v[170:173], v[24:27]
	v_mfma_f32_16x16x32_bf16 v[20:23], v[154:157], v[178:181], v[20:23]
	v_mfma_f32_16x16x32_bf16 v[16:19], v[162:165], v[178:181], v[16:19]
	v_mfma_f32_16x16x32_bf16 v[12:15], v[154:157], v[186:189], v[12:15]
	v_mfma_f32_16x16x32_bf16 v[8:11], v[162:165], v[186:189], v[8:11]
	v_mfma_f32_16x16x32_bf16 v[4:7], v[154:157], v[194:197], v[4:7]
	v_mfma_f32_16x16x32_bf16 v[0:3], v[162:165], v[194:197], v[0:3]
	v_mfma_f32_16x16x32_bf16 v[28:31], v[158:161], v[174:177], v[28:31]
	v_mfma_f32_16x16x32_bf16 v[24:27], v[166:169], v[174:177], v[24:27]
	v_mfma_f32_16x16x32_bf16 v[20:23], v[158:161], v[182:185], v[20:23]
	v_mfma_f32_16x16x32_bf16 v[16:19], v[166:169], v[182:185], v[16:19]
	v_mfma_f32_16x16x32_bf16 v[12:15], v[158:161], v[190:193], v[12:15]
	v_mfma_f32_16x16x32_bf16 v[8:11], v[166:169], v[190:193], v[8:11]
	v_mfma_f32_16x16x32_bf16 v[4:7], v[158:161], v[198:201], v[4:7]
	v_mfma_f32_16x16x32_bf16 v[0:3], v[166:169], v[198:201], v[0:3]
	s_setprio 0
	s_barrier
	s_add_i32 s63, s63, 2
	s_add_u32 s9, s9, 0x10000
	s_addc_u32 s33, s33, 0
	s_add_u32 s47, s47, 0x100
	s_addc_u32 s62, s62, 0
	s_cmp_gt_u32 s63, 29
	s_cbranch_scc0 .LBB0_485
	s_and_b64 vcc, exec, s[44:45]
	s_cbranch_vccz .LBB0_488
	s_barrier

; #define PG8_STAGE(bufoff, gbase, voff) do { const __amdgpu_buffer_rsrc_t _rs = __builtin_amdgcn_make_buffer_rsrc((void*)(gbase), 0, 0x7fffffff, 0x00020000); _Pragma("unroll") for (int _i = 0; _i < 2; ++_i) \
;         __builtin_amdgcn_raw_ptr_buffer_load_lds(_rs, (LAS unsigned*)(lds + (bufoff) + ldsw + _i * 8192), 16, (int)(voff)[_i], 0, 0, 0); } while (0)
; #define PG8_WAIT_V(n) asm volatile("s_waitcnt vmcnt(" #n ")" ::: "memory")
; #define PG8_WAIT_L(n) asm volatile("s_waitcnt lgkmcnt(" #n ")" ::: "memory")
; #define PG8_BAR __builtin_amdgcn_s_barrier()
; #define PG8_SCHED __builtin_amdgcn_sched_barrier(0)
; template <class Epi, class Sched, bool F8 = false>
; __device__ __forceinline__ void gemm_phase(LAS unsigned char* lds, const int lda, const int ldb, const Sched& S, const Epi& E) {
;     ...
;             const bool last = (t == nt - 2);
;             const char* a1 = cA + (size_t)(t + 1) * kstep;
;             const char* a2 = last ? nA : cA + (size_t)(t + 2) * kstep; const char* b2 = last ? nB : cB + (size_t)(t + 2) * kstepB;
;             const char* a3 = a2 + kstep; const char* b3 = b2 + kstepB;
;     ...
;             PG8_LDB(B0, 0, 0); PG8_LDB(B1, 0, 1); PG8_SCHED; PG8_LDA(At, 0, 0); PG8_STAGE(PG8_SA(1, 1), a1 + hstepA, voffA);
;             PG8_WAIT_V(8); PG8_WAIT_L(0); PG8_BAR; PG8_MMA(0, 0, At, B0); PG8_MMA(0, 1, At, B1); PG8_BAR; PG8_SCHED;
;             PG8_LDA(At, 0, 1); PG8_STAGE(PG8_SB(0, 0), b2, voffB); PG8_STAGE(PG8_SB(0, 1), b2 + hstepB, voffB); PG8_STAGE(PG8_SA(0, 0), a2, voffA);
;             PG8_WAIT_V(8); PG8_WAIT_L(0); PG8_BAR; PG8_MMA(1, 0, At, B0); PG8_MMA(1, 1, At, B1); PG8_BAR; PG8_SCHED;
.LBB0_632:
	ds_read_b128 v[132:135], v142
	ds_read_b128 v[148:151], v142 offset:1024
	ds_read_b128 v[152:155], v142 offset:2048
	ds_read_b128 v[156:159], v142 offset:3072
	ds_read_b128 v[160:163], v143
	ds_read_b128 v[164:167], v143 offset:1024
	ds_read_b128 v[168:171], v143 offset:2048
	ds_read_b128 v[172:175], v143 offset:3072
	s_add_u32 s4, vcc_lo, 0xfff00080
	s_addc_u32 s5, vcc_hi, -1
	s_cmp_eq_u32 s64, 60
	s_cselect_b32 s40, s68, s4
	s_cselect_b32 s19, s69, s5
	s_cselect_b32 s18, s71, s67
	s_cselect_b32 s36, s70, s51
	s_add_u32 s16, s40, 0x80
	s_addc_u32 s17, s19, 0
	s_and_b32 s5, vcc_hi, 0xffff
	s_mov_b32 s4, vcc_lo
	s_mov_b32 m0, s92
	ds_read_b128 v[176:179], v144
	ds_read_b128 v[180:183], v144 offset:1024
	ds_read_b128 v[184:187], v144 offset:2048
	ds_read_b128 v[188:191], v144 offset:3072
	ds_read_b128 v[192:195], v144 offset:4096
	ds_read_b128 v[196:199], v144 offset:5120
	ds_read_b128 v[200:203], v144 offset:6144
	ds_read_b128 v[204:207], v144 offset:7168
	buffer_load_dwordx4 v138, s[4:7], 0 offen lds
	s_mov_b32 m0, s93
	s_nop 0
	buffer_load_dwordx4 v140, s[4:7], 0 offen lds
	s_waitcnt vmcnt(8)
	s_waitcnt lgkmcnt(0)
	s_barrier
	s_setprio 1
	v_mfma_f32_16x16x32_bf16 v[124:127], v[132:135], v[176:179], v[124:127]
	v_mfma_f32_16x16x32_bf16 v[120:123], v[152:155], v[176:179], v[120:123]
	v_mfma_f32_16x16x32_bf16 v[108:111], v[132:135], v[184:187], v[108:111]
	v_mfma_f32_16x16x32_bf16 v[104:107], v[152:155], v[184:187], v[104:107]
	v_mfma_f32_16x16x32_bf16 v[92:95], v[132:135], v[192:195], v[92:95]
	v_mfma_f32_16x16x32_bf16 v[88:91], v[152:155], v[192:195], v[88:91]
	v_mfma_f32_16x16x32_bf16 v[76:79], v[132:135], v[200:203], v[76:79]
	v_mfma_f32_16x16x32_bf16 v[72:75], v[152:155], v[200:203], v[72:75]
	v_mfma_f32_16x16x32_bf16 v[124:127], v[148:151], v[180:183], v[124:127]
	v_mfma_f32_16x16x32_bf16 v[120:123], v[156:159], v[180:183], v[120:123]
	v_mfma_f32_16x16x32_bf16 v[108:111], v[148:151], v[188:191], v[108:111]
	v_mfma_f32_16x16x32_bf16 v[104:107], v[156:159], v[188:191], v[104:107]
	v_mfma_f32_16x16x32_bf16 v[92:95], v[148:151], v[196:199], v[92:95]
	v_mfma_f32_16x16x32_bf16 v[88:91], v[156:159], v[196:199], v[88:91]
	v_mfma_f32_16x16x32_bf16 v[76:79], v[148:151], v[204:207], v[76:79]
	v_mfma_f32_16x16x32_bf16 v[72:75], v[156:159], v[204:207], v[72:75]
	s_setprio 0
	s_setprio 1
	v_mfma_f32_16x16x32_bf16 v[116:119], v[160:163], v[176:179], v[116:119]
	v_mfma_f32_16x16x32_bf16 v[112:115], v[168:171], v[176:179], v[112:115]
	v_mfma_f32_16x16x32_bf16 v[100:103], v[160:163], v[184:187], v[100:103]
	v_mfma_f32_16x16x32_bf16 v[96:99], v[168:171], v[184:187], v[96:99]
	v_mfma_f32_16x16x32_bf16 v[84:87], v[160:163], v[192:195], v[84:87]
	v_mfma_f32_16x16x32_bf16 v[80:83], v[168:171], v[192:195], v[80:83]
	v_mfma_f32_16x16x32_bf16 v[68:71], v[160:163], v[200:203], v[68:71]
	v_mfma_f32_16x16x32_bf16 v[64:67], v[168:171], v[200:203], v[64:67]
	v_mfma_f32_16x16x32_bf16 v[116:119], v[164:167], v[180:183], v[116:119]
	v_mfma_f32_16x16x32_bf16 v[112:115], v[172:175], v[180:183], v[112:115]
	v_mfma_f32_16x16x32_bf16 v[100:103], v[164:167], v[188:191], v[100:103]
	v_mfma_f32_16x16x32_bf16 v[96:99], v[172:175], v[188:191], v[96:99]
	v_mfma_f32_16x16x32_bf16 v[84:87], v[164:167], v[196:199], v[84:87]
	v_mfma_f32_16x16x32_bf16 v[80:83], v[172:175], v[196:199], v[80:83]
	v_mfma_f32_16x16x32_bf16 v[68:71], v[164:167], v[204:207], v[68:71]
	v_mfma_f32_16x16x32_bf16 v[64:67], v[172:175], v[204:207], v[64:67]
	s_setprio 0
	s_barrier
	s_and_b32 s37, s18, 0xffff
	s_mov_b32 m0, s73
	s_mov_b32 s38, s6
	s_mov_b32 s39, s7
	s_add_u32 s4, s36, 0x4000
	ds_read_b128 v[176:179], v144 offset:16384
	ds_read_b128 v[180:183], v144 offset:17408
	ds_read_b128 v[184:187], v144 offset:18432
	ds_read_b128 v[188:191], v144 offset:19456
	ds_read_b128 v[192:195], v144 offset:20480
	ds_read_b128 v[196:199], v144 offset:21504
	ds_read_b128 v[200:203], v144 offset:22528
	ds_read_b128 v[204:207], v144 offset:23552
	buffer_load_dwordx4 v139, s[36:39], 0 offen lds
	s_mov_b32 m0, s74
	s_addc_u32 s5, s18, 0
	buffer_load_dwordx4 v141, s[36:39], 0 offen lds
	s_and_b32 s5, s5, 0xffff
	s_mov_b32 m0, s75
	s_and_b32 s41, s19, 0xffff
	buffer_load_dwordx4 v139, s[4:7], 0 offen lds
	s_mov_b32 m0, s76
	s_mov_b32 s42, s6
	buffer_load_dwordx4 v141, s[4:7], 0 offen lds
	s_mov_b32 s43, s7
	s_mov_b32 m0, s61
	s_nop 0
	buffer_load_dwordx4 v138, s[40:43], 0 offen lds
	s_mov_b32 m0, s77
	s_nop 0
	buffer_load_dwordx4 v140, s[40:43], 0 offen lds
	s_waitcnt vmcnt(8)
	s_waitcnt lgkmcnt(0)
	s_barrier
; #define PG8_STAGE(bufoff, gbase, voff) do { const __amdgpu_buffer_rsrc_t _rs = __builtin_amdgcn_make_buffer_rsrc((void*)(gbase), 0, 0x7fffffff, 0x00020000); _Pragma("unroll") for (int _i = 0; _i < 2; ++_i) \
;         __builtin_amdgcn_raw_ptr_buffer_load_lds(_rs, (LAS unsigned*)(lds + (bufoff) + ldsw + _i * 8192), 16, (int)(voff)[_i], 0, 0, 0); } while (0)
; #define PG8_WAIT_V(n) asm volatile("s_waitcnt vmcnt(" #n ")" ::: "memory")
; #define PG8_WAIT_L(n) asm volatile("s_waitcnt lgkmcnt(" #n ")" ::: "memory")
; #define PG8_BAR __builtin_amdgcn_s_barrier()
; #define PG8_SCHED __builtin_amdgcn_sched_barrier(0)
; template <class Epi, class Sched, bool F8 = false>
; __device__ __forceinline__ void gemm_phase(LAS unsigned char* lds, const int lda, const int ldb, const Sched& S, const Epi& E) {
;     ...
;             PG8_WAIT_V(8); PG8_WAIT_L(0); PG8_BAR; PG8_MMA(1, 0, At, B0); PG8_MMA(1, 1, At, B1); PG8_BAR; PG8_SCHED;
;             PG8_LDB(B0, 1, 0); PG8_LDB(B1, 1, 1); PG8_SCHED; PG8_LDA(At, 1, 0); PG8_STAGE(PG8_SA(0, 1), a2 + hstepA, voffA);
;             PG8_WAIT_V(8); PG8_WAIT_L(0); PG8_BAR; PG8_MMA(0, 0, At, B0); PG8_MMA(0, 1, At, B1); PG8_BAR; PG8_SCHED;
	s_setprio 1
	v_mfma_f32_16x16x32_bf16 v[60:63], v[132:135], v[176:179], v[60:63]
	v_mfma_f32_16x16x32_bf16 v[56:59], v[152:155], v[176:179], v[56:59]
	v_mfma_f32_16x16x32_bf16 v[44:47], v[132:135], v[184:187], v[44:47]
	v_mfma_f32_16x16x32_bf16 v[40:43], v[152:155], v[184:187], v[40:43]
	v_mfma_f32_16x16x32_bf16 v[28:31], v[132:135], v[192:195], v[28:31]
	v_mfma_f32_16x16x32_bf16 v[24:27], v[152:155], v[192:195], v[24:27]
	v_mfma_f32_16x16x32_bf16 v[12:15], v[132:135], v[200:203], v[12:15]
	v_mfma_f32_16x16x32_bf16 v[8:11], v[152:155], v[200:203], v[8:11]
	v_mfma_f32_16x16x32_bf16 v[60:63], v[148:151], v[180:183], v[60:63]
	v_mfma_f32_16x16x32_bf16 v[56:59], v[156:159], v[180:183], v[56:59]
	v_mfma_f32_16x16x32_bf16 v[44:47], v[148:151], v[188:191], v[44:47]
	v_mfma_f32_16x16x32_bf16 v[40:43], v[156:159], v[188:191], v[40:43]
	v_mfma_f32_16x16x32_bf16 v[28:31], v[148:151], v[196:199], v[28:31]
	v_mfma_f32_16x16x32_bf16 v[24:27], v[156:159], v[196:199], v[24:27]
	v_mfma_f32_16x16x32_bf16 v[12:15], v[148:151], v[204:207], v[12:15]
	v_mfma_f32_16x16x32_bf16 v[8:11], v[156:159], v[204:207], v[8:11]
	s_setprio 0
	s_setprio 1
	v_mfma_f32_16x16x32_bf16 v[52:55], v[160:163], v[176:179], v[52:55]
	v_mfma_f32_16x16x32_bf16 v[48:51], v[168:171], v[176:179], v[48:51]
	v_mfma_f32_16x16x32_bf16 v[36:39], v[160:163], v[184:187], v[36:39]
	v_mfma_f32_16x16x32_bf16 v[32:35], v[168:171], v[184:187], v[32:35]
	v_mfma_f32_16x16x32_bf16 v[20:23], v[160:163], v[192:195], v[20:23]
	v_mfma_f32_16x16x32_bf16 v[16:19], v[168:171], v[192:195], v[16:19]
	v_mfma_f32_16x16x32_bf16 v[4:7], v[160:163], v[200:203], v[4:7]
	v_mfma_f32_16x16x32_bf16 v[0:3], v[168:171], v[200:203], v[0:3]
	v_mfma_f32_16x16x32_bf16 v[52:55], v[164:167], v[180:183], v[52:55]
	v_mfma_f32_16x16x32_bf16 v[48:51], v[172:175], v[180:183], v[48:51]
	v_mfma_f32_16x16x32_bf16 v[36:39], v[164:167], v[188:191], v[36:39]
	v_mfma_f32_16x16x32_bf16 v[32:35], v[172:175], v[188:191], v[32:35]
	v_mfma_f32_16x16x32_bf16 v[20:23], v[164:167], v[196:199], v[20:23]
	v_mfma_f32_16x16x32_bf16 v[16:19], v[172:175], v[196:199], v[16:19]
	v_mfma_f32_16x16x32_bf16 v[4:7], v[164:167], v[204:207], v[4:7]
	v_mfma_f32_16x16x32_bf16 v[0:3], v[172:175], v[204:207], v[0:3]
	s_setprio 0
	s_barrier
	ds_read_b128 v[132:135], v145
	ds_read_b128 v[148:151], v145 offset:1024
	ds_read_b128 v[152:155], v145 offset:2048
	ds_read_b128 v[156:159], v145 offset:3072
	ds_read_b128 v[160:163], v146
	ds_read_b128 v[164:167], v146 offset:1024
	ds_read_b128 v[168:171], v146 offset:2048
	ds_read_b128 v[172:175], v146 offset:3072
	s_add_u32 s4, s40, 0x100000
	s_addc_u32 s5, s19, 0
	s_and_b32 s5, s5, 0xffff
	s_mov_b32 m0, s78
	ds_read_b128 v[176:179], v144 offset:32768
	ds_read_b128 v[180:183], v144 offset:33792
	ds_read_b128 v[184:187], v144 offset:34816
	ds_read_b128 v[188:191], v144 offset:35840
	ds_read_b128 v[192:195], v144 offset:36864
	ds_read_b128 v[196:199], v144 offset:37888
	ds_read_b128 v[200:203], v144 offset:38912
	ds_read_b128 v[204:207], v144 offset:39936
	buffer_load_dwordx4 v138, s[4:7], 0 offen lds
	s_mov_b32 m0, s79
	s_nop 0
	buffer_load_dwordx4 v140, s[4:7], 0 offen lds
	s_waitcnt vmcnt(8)
	s_waitcnt lgkmcnt(0)
	s_barrier
	s_setprio 1
	v_mfma_f32_16x16x32_bf16 v[124:127], v[132:135], v[176:179], v[124:127]
	v_mfma_f32_16x16x32_bf16 v[120:123], v[152:155], v[176:179], v[120:123]
	v_mfma_f32_16x16x32_bf16 v[108:111], v[132:135], v[184:187], v[108:111]
	v_mfma_f32_16x16x32_bf16 v[104:107], v[152:155], v[184:187], v[104:107]
	v_mfma_f32_16x16x32_bf16 v[92:95], v[132:135], v[192:195], v[92:95]
	v_mfma_f32_16x16x32_bf16 v[88:91], v[152:155], v[192:195], v[88:91]
	v_mfma_f32_16x16x32_bf16 v[76:79], v[132:135], v[200:203], v[76:79]
	v_mfma_f32_16x16x32_bf16 v[72:75], v[152:155], v[200:203], v[72:75]
	v_mfma_f32_16x16x32_bf16 v[124:127], v[148:151], v[180:183], v[124:127]
	v_mfma_f32_16x16x32_bf16 v[120:123], v[156:159], v[180:183], v[120:123]
	v_mfma_f32_16x16x32_bf16 v[108:111], v[148:151], v[188:191], v[108:111]
	v_mfma_f32_16x16x32_bf16 v[104:107], v[156:159], v[188:191], v[104:107]
	v_mfma_f32_16x16x32_bf16 v[92:95], v[148:151], v[196:199], v[92:95]
	v_mfma_f32_16x16x32_bf16 v[88:91], v[156:159], v[196:199], v[88:91]
	v_mfma_f32_16x16x32_bf16 v[76:79], v[148:151], v[204:207], v[76:79]
	v_mfma_f32_16x16x32_bf16 v[72:75], v[156:159], v[204:207], v[72:75]
	s_setprio 0
	s_setprio 1
	v_mfma_f32_16x16x32_bf16 v[116:119], v[160:163], v[176:179], v[116:119]
	v_mfma_f32_16x16x32_bf16 v[112:115], v[168:171], v[176:179], v[112:115]
	v_mfma_f32_16x16x32_bf16 v[100:103], v[160:163], v[184:187], v[100:103]
	v_mfma_f32_16x16x32_bf16 v[96:99], v[168:171], v[184:187], v[96:99]
	v_mfma_f32_16x16x32_bf16 v[84:87], v[160:163], v[192:195], v[84:87]
	v_mfma_f32_16x16x32_bf16 v[80:83], v[168:171], v[192:195], v[80:83]
	v_mfma_f32_16x16x32_bf16 v[68:71], v[160:163], v[200:203], v[68:71]
	v_mfma_f32_16x16x32_bf16 v[64:67], v[168:171], v[200:203], v[64:67]
	v_mfma_f32_16x16x32_bf16 v[116:119], v[164:167], v[180:183], v[116:119]
	v_mfma_f32_16x16x32_bf16 v[112:115], v[172:175], v[180:183], v[112:115]
	v_mfma_f32_16x16x32_bf16 v[100:103], v[164:167], v[188:191], v[100:103]
	v_mfma_f32_16x16x32_bf16 v[96:99], v[172:175], v[188:191], v[96:99]
	v_mfma_f32_16x16x32_bf16 v[84:87], v[164:167], v[196:199], v[84:87]
	v_mfma_f32_16x16x32_bf16 v[80:83], v[172:175], v[196:199], v[80:83]
	v_mfma_f32_16x16x32_bf16 v[68:71], v[164:167], v[204:207], v[68:71]
	v_mfma_f32_16x16x32_bf16 v[64:67], v[172:175], v[204:207], v[64:67]
	s_setprio 0
	s_barrier
; #define PG8_STAGE(bufoff, gbase, voff) do { const __amdgpu_buffer_rsrc_t _rs = __builtin_amdgcn_make_buffer_rsrc((void*)(gbase), 0, 0x7fffffff, 0x00020000); _Pragma("unroll") for (int _i = 0; _i < 2; ++_i) \
;         __builtin_amdgcn_raw_ptr_buffer_load_lds(_rs, (LAS unsigned*)(lds + (bufoff) + ldsw + _i * 8192), 16, (int)(voff)[_i], 0, 0, 0); } while (0)
; #define PG8_WAIT_V(n) asm volatile("s_waitcnt vmcnt(" #n ")" ::: "memory")
; #define PG8_WAIT_L(n) asm volatile("s_waitcnt lgkmcnt(" #n ")" ::: "memory")
; #define PG8_BAR __builtin_amdgcn_s_barrier()
; #define PG8_SCHED __builtin_amdgcn_sched_barrier(0)
; template <class Epi, class Sched, bool F8 = false>
; __device__ __forceinline__ void gemm_phase(LAS unsigned char* lds, const int lda, const int ldb, const Sched& S, const Epi& E) {
;     ...
;             PG8_LDA(At, 1, 1); PG8_STAGE(PG8_SB(1, 0), b3, voffB); PG8_STAGE(PG8_SB(1, 1), b3 + hstepB, voffB); PG8_STAGE(PG8_SA(1, 0), a3, voffA);
;             PG8_WAIT_V(8); PG8_WAIT_L(0); PG8_BAR; PG8_MMA(1, 0, At, B0); PG8_MMA(1, 1, At, B1); PG8_BAR; PG8_SCHED;
	s_add_u32 s4, s36, 0x8000
	s_addc_u32 s5, s18, 0
	s_mov_b32 m0, s86
	s_and_b32 s5, s5, 0xffff
	ds_read_b128 v[176:179], v144 offset:49152
	ds_read_b128 v[180:183], v144 offset:50176
	ds_read_b128 v[184:187], v144 offset:51200
	ds_read_b128 v[188:191], v144 offset:52224
	ds_read_b128 v[192:195], v144 offset:53248
	ds_read_b128 v[196:199], v144 offset:54272
	ds_read_b128 v[200:203], v144 offset:55296
	ds_read_b128 v[204:207], v144 offset:56320
	buffer_load_dwordx4 v139, s[4:7], 0 offen lds
	s_mov_b32 m0, s87
	s_mov_b32 s19, s7
	buffer_load_dwordx4 v141, s[4:7], 0 offen lds
	s_add_u32 s4, s36, 0xc000
	s_addc_u32 s5, s18, 0
	s_and_b32 s5, s5, 0xffff
	s_mov_b32 m0, s90
	s_and_b32 s17, s17, 0xffff
	buffer_load_dwordx4 v139, s[4:7], 0 offen lds
	s_mov_b32 m0, s91
	s_mov_b32 s18, s6
	buffer_load_dwordx4 v141, s[4:7], 0 offen lds
	s_mov_b32 m0, s88
	s_nop 0
	buffer_load_dwordx4 v138, s[16:19], 0 offen lds
	s_mov_b32 m0, s89
	s_nop 0
	buffer_load_dwordx4 v140, s[16:19], 0 offen lds
	s_waitcnt vmcnt(8)
	s_waitcnt lgkmcnt(0)
	s_barrier
	s_setprio 1
	v_mfma_f32_16x16x32_bf16 v[60:63], v[132:135], v[176:179], v[60:63]
	v_mfma_f32_16x16x32_bf16 v[56:59], v[152:155], v[176:179], v[56:59]
	v_mfma_f32_16x16x32_bf16 v[44:47], v[132:135], v[184:187], v[44:47]
	v_mfma_f32_16x16x32_bf16 v[40:43], v[152:155], v[184:187], v[40:43]
	v_mfma_f32_16x16x32_bf16 v[28:31], v[132:135], v[192:195], v[28:31]
	v_mfma_f32_16x16x32_bf16 v[24:27], v[152:155], v[192:195], v[24:27]
	v_mfma_f32_16x16x32_bf16 v[12:15], v[132:135], v[200:203], v[12:15]
	v_mfma_f32_16x16x32_bf16 v[8:11], v[152:155], v[200:203], v[8:11]
	v_mfma_f32_16x16x32_bf16 v[60:63], v[148:151], v[180:183], v[60:63]
	v_mfma_f32_16x16x32_bf16 v[56:59], v[156:159], v[180:183], v[56:59]
	v_mfma_f32_16x16x32_bf16 v[44:47], v[148:151], v[188:191], v[44:47]
	v_mfma_f32_16x16x32_bf16 v[40:43], v[156:159], v[188:191], v[40:43]
	v_mfma_f32_16x16x32_bf16 v[28:31], v[148:151], v[196:199], v[28:31]
	v_mfma_f32_16x16x32_bf16 v[24:27], v[156:159], v[196:199], v[24:27]
	v_mfma_f32_16x16x32_bf16 v[12:15], v[148:151], v[204:207], v[12:15]
	v_mfma_f32_16x16x32_bf16 v[8:11], v[156:159], v[204:207], v[8:11]
	s_setprio 0
	s_setprio 1
	v_mfma_f32_16x16x32_bf16 v[52:55], v[160:163], v[176:179], v[52:55]
	v_mfma_f32_16x16x32_bf16 v[48:51], v[168:171], v[176:179], v[48:51]
	v_mfma_f32_16x16x32_bf16 v[36:39], v[160:163], v[184:187], v[36:39]
	v_mfma_f32_16x16x32_bf16 v[32:35], v[168:171], v[184:187], v[32:35]
	v_mfma_f32_16x16x32_bf16 v[20:23], v[160:163], v[192:195], v[20:23]
	v_mfma_f32_16x16x32_bf16 v[16:19], v[168:171], v[192:195], v[16:19]
	v_mfma_f32_16x16x32_bf16 v[4:7], v[160:163], v[200:203], v[4:7]
	v_mfma_f32_16x16x32_bf16 v[0:3], v[168:171], v[200:203], v[0:3]
	v_mfma_f32_16x16x32_bf16 v[52:55], v[164:167], v[180:183], v[52:55]
	v_mfma_f32_16x16x32_bf16 v[48:51], v[172:175], v[180:183], v[48:51]
	v_mfma_f32_16x16x32_bf16 v[36:39], v[164:167], v[188:191], v[36:39]
	v_mfma_f32_16x16x32_bf16 v[32:35], v[172:175], v[188:191], v[32:35]
	v_mfma_f32_16x16x32_bf16 v[20:23], v[164:167], v[196:199], v[20:23]
	v_mfma_f32_16x16x32_bf16 v[16:19], v[172:175], v[196:199], v[16:19]
	v_mfma_f32_16x16x32_bf16 v[4:7], v[164:167], v[204:207], v[4:7]
	v_mfma_f32_16x16x32_bf16 v[0:3], v[172:175], v[204:207], v[0:3]
	s_setprio 0
	s_barrier
	s_add_i32 s64, s64, 2
	s_add_u32 s51, s51, 0x10000
	s_addc_u32 s67, s67, 0
	s_add_u32 vcc_lo, vcc_lo, 0x100
	s_addc_u32 vcc_hi, vcc_hi, 0
	s_cmp_gt_u32 s64, 61
	s_cbranch_scc0 .LBB0_632
	s_and_b64 vcc, exec, s[26:27]
	s_cbranch_vccz .LBB0_635
	s_barrier

; #define PG8_STAGE(bufoff, gbase, voff) do { const __amdgpu_buffer_rsrc_t _rs = __builtin_amdgcn_make_buffer_rsrc((void*)(gbase), 0, 0x7fffffff, 0x00020000); _Pragma("unroll") for (int _i = 0; _i < 2; ++_i) \
;         __builtin_amdgcn_raw_ptr_buffer_load_lds(_rs, (LAS unsigned*)(lds + (bufoff) + ldsw + _i * 8192), 16, (int)(voff)[_i], 0, 0, 0); } while (0)
; #define PG8_WAIT_V(n) asm volatile("s_waitcnt vmcnt(" #n ")" ::: "memory")
; #define PG8_WAIT_L(n) asm volatile("s_waitcnt lgkmcnt(" #n ")" ::: "memory")
; #define PG8_BAR __builtin_amdgcn_s_barrier()
; #define PG8_SCHED __builtin_amdgcn_sched_barrier(0)
; template <class Epi, class Sched, bool F8 = false>
; __device__ __forceinline__ void gemm_phase(LAS unsigned char* lds, const int lda, const int ldb, const Sched& S, const Epi& E) {
;     ...
;             const bool last = (t == nt - 2);
;             const char* a1 = cA + (size_t)(t + 1) * kstep;
;             const char* a2 = last ? nA : cA + (size_t)(t + 2) * kstep; const char* b2 = last ? nB : cB + (size_t)(t + 2) * kstepB;
;             const char* a3 = a2 + kstep; const char* b3 = b2 + kstepB;
;     ...
;             PG8_LDB(B0, 0, 0); PG8_LDB(B1, 0, 1); PG8_SCHED; PG8_LDA(At, 0, 0); PG8_STAGE(PG8_SA(1, 1), a1 + hstepA, voffA);
;             PG8_WAIT_V(8); PG8_WAIT_L(0); PG8_BAR; PG8_MMA(0, 0, At, B0); PG8_MMA(0, 1, At, B1); PG8_BAR; PG8_SCHED;
;             PG8_LDA(At, 0, 1); PG8_STAGE(PG8_SB(0, 0), b2, voffB); PG8_STAGE(PG8_SB(0, 1), b2 + hstepB, voffB); PG8_STAGE(PG8_SA(0, 0), a2, voffA);
;             PG8_WAIT_V(8); PG8_WAIT_L(0); PG8_BAR; PG8_MMA(1, 0, At, B0); PG8_MMA(1, 1, At, B1); PG8_BAR; PG8_SCHED;
.LBB0_778:
	ds_read_b128 v[118:121], v194
	ds_read_b128 v[122:125], v194 offset:1024
	ds_read_b128 v[130:133], v194 offset:2048
	ds_read_b128 v[134:137], v194 offset:3072
	ds_read_b128 v[138:141], v195
	ds_read_b128 v[142:145], v195 offset:1024
	ds_read_b128 v[146:149], v195 offset:2048
	ds_read_b128 v[150:153], v195 offset:3072
	s_add_u32 s4, s33, 0xfff00080
	s_addc_u32 s5, s43, -1
	s_cmp_eq_u32 s45, 60
	s_cselect_b32 s20, s46, s4
	s_cselect_b32 s7, s47, s5
	s_cselect_b32 s6, s49, s9
	s_cselect_b32 s16, s48, s8
	s_add_u32 s4, s20, 0x80
	s_addc_u32 s5, s7, 0
	s_and_b32 s13, s43, 0xffff
	s_mov_b32 s12, s33
	s_mov_b32 m0, s84
	ds_read_b128 v[162:165], v196
	ds_read_b128 v[166:169], v196 offset:1024
	ds_read_b128 v[170:173], v196 offset:2048
	ds_read_b128 v[186:189], v196 offset:3072
	ds_read_b128 v[200:203], v196 offset:4096
	ds_read_b128 v[204:207], v196 offset:5120
	ds_read_b128 v[208:211], v196 offset:6144
	ds_read_b128 v[212:215], v196 offset:7168
	buffer_load_dwordx4 v175, s[12:15], 0 offen lds
	s_mov_b32 m0, s86
	s_nop 0
	buffer_load_dwordx4 v179, s[12:15], 0 offen lds
	s_waitcnt vmcnt(8)
	s_waitcnt lgkmcnt(0)
	s_barrier
	s_setprio 1
	v_mfma_f32_16x16x32_bf16 v[158:161], v[118:121], v[162:165], v[158:161]
	v_mfma_f32_16x16x32_bf16 v[60:63], v[130:133], v[162:165], v[60:63]
	v_mfma_f32_16x16x32_bf16 v[154:157], v[118:121], v[170:173], v[154:157]
	v_mfma_f32_16x16x32_bf16 v[52:55], v[130:133], v[170:173], v[52:55]
	v_mfma_f32_16x16x32_bf16 v[114:117], v[118:121], v[200:203], v[114:117]
	v_mfma_f32_16x16x32_bf16 v[44:47], v[130:133], v[200:203], v[44:47]
	v_mfma_f32_16x16x32_bf16 v[108:111], v[118:121], v[208:211], v[110:113]
	v_mfma_f32_16x16x32_bf16 v[36:39], v[130:133], v[208:211], v[36:39]
	v_mfma_f32_16x16x32_bf16 v[158:161], v[122:125], v[166:169], v[158:161]
	v_mfma_f32_16x16x32_bf16 v[60:63], v[134:137], v[166:169], v[60:63]
	v_mfma_f32_16x16x32_bf16 v[154:157], v[122:125], v[186:189], v[154:157]
	v_mfma_f32_16x16x32_bf16 v[52:55], v[134:137], v[186:189], v[52:55]
	v_mfma_f32_16x16x32_bf16 v[114:117], v[122:125], v[204:207], v[114:117]
	v_mfma_f32_16x16x32_bf16 v[44:47], v[134:137], v[204:207], v[44:47]
	v_mfma_f32_16x16x32_bf16 v[108:111], v[122:125], v[212:215], v[108:111]
	v_mfma_f32_16x16x32_bf16 v[36:39], v[134:137], v[212:215], v[36:39]
	s_setprio 0
	s_setprio 1
	v_mfma_f32_16x16x32_bf16 v[104:107], v[138:141], v[162:165], v[104:107]
	v_mfma_f32_16x16x32_bf16 v[56:59], v[146:149], v[162:165], v[56:59]
	v_mfma_f32_16x16x32_bf16 v[126:129], v[138:141], v[170:173], v[126:129]
	v_mfma_f32_16x16x32_bf16 v[48:51], v[146:149], v[170:173], v[48:51]
	v_mfma_f32_16x16x32_bf16 v[100:103], v[138:141], v[200:203], v[100:103]
	v_mfma_f32_16x16x32_bf16 v[40:43], v[146:149], v[200:203], v[40:43]
	v_mfma_f32_16x16x32_bf16 v[96:99], v[138:141], v[208:211], v[96:99]
	v_mfma_f32_16x16x32_bf16 v[32:35], v[146:149], v[208:211], v[32:35]
	v_mfma_f32_16x16x32_bf16 v[104:107], v[142:145], v[166:169], v[104:107]
	v_mfma_f32_16x16x32_bf16 v[56:59], v[150:153], v[166:169], v[56:59]
	v_mfma_f32_16x16x32_bf16 v[126:129], v[142:145], v[186:189], v[126:129]
	v_mfma_f32_16x16x32_bf16 v[48:51], v[150:153], v[186:189], v[48:51]
	v_mfma_f32_16x16x32_bf16 v[100:103], v[142:145], v[204:207], v[100:103]
	v_mfma_f32_16x16x32_bf16 v[40:43], v[150:153], v[204:207], v[40:43]
	v_mfma_f32_16x16x32_bf16 v[96:99], v[142:145], v[212:215], v[96:99]
	v_mfma_f32_16x16x32_bf16 v[32:35], v[150:153], v[212:215], v[32:35]
	s_setprio 0
	s_barrier
	s_and_b32 s17, s6, 0xffff
	s_mov_b32 m0, s68
	s_mov_b32 s18, s14
	s_mov_b32 s19, s15
	s_add_u32 s12, s16, 0x4000
	ds_read_b128 v[162:165], v196 offset:16384
	ds_read_b128 v[166:169], v196 offset:17408
	ds_read_b128 v[170:173], v196 offset:18432
	ds_read_b128 v[186:189], v196 offset:19456
	ds_read_b128 v[200:203], v196 offset:20480
	ds_read_b128 v[204:207], v196 offset:21504
	ds_read_b128 v[208:211], v196 offset:22528
	ds_read_b128 v[212:215], v196 offset:23552
	buffer_load_dwordx4 v177, s[16:19], 0 offen lds
	s_mov_b32 m0, s69
	s_addc_u32 s13, s6, 0
	buffer_load_dwordx4 v193, s[16:19], 0 offen lds
	s_and_b32 s13, s13, 0xffff
	s_mov_b32 m0, s70
	s_and_b32 s21, s7, 0xffff
	buffer_load_dwordx4 v177, s[12:15], 0 offen lds
	s_mov_b32 m0, s71
	s_mov_b32 s22, s14
	buffer_load_dwordx4 v193, s[12:15], 0 offen lds
	s_mov_b32 s23, s15
	s_mov_b32 m0, s51
	s_nop 0
	buffer_load_dwordx4 v175, s[20:23], 0 offen lds
	s_mov_b32 m0, s72
	s_nop 0
	buffer_load_dwordx4 v179, s[20:23], 0 offen lds
	s_waitcnt vmcnt(8)
	s_waitcnt lgkmcnt(0)
	s_barrier
	s_setprio 1
	v_mfma_f32_16x16x32_bf16 v[92:95], v[118:121], v[162:165], v[92:95]
	v_mfma_f32_16x16x32_bf16 v[28:31], v[130:133], v[162:165], v[28:31]
	v_mfma_f32_16x16x32_bf16 v[84:87], v[118:121], v[170:173], v[84:87]
	v_mfma_f32_16x16x32_bf16 v[20:23], v[130:133], v[170:173], v[20:23]
	v_mfma_f32_16x16x32_bf16 v[76:79], v[118:121], v[200:203], v[76:79]
	v_mfma_f32_16x16x32_bf16 v[12:15], v[130:133], v[200:203], v[12:15]
	v_mfma_f32_16x16x32_bf16 v[72:75], v[118:121], v[208:211], v[72:75]
	v_mfma_f32_16x16x32_bf16 v[4:7], v[130:133], v[208:211], v[4:7]
	v_mfma_f32_16x16x32_bf16 v[92:95], v[122:125], v[166:169], v[92:95]
	v_mfma_f32_16x16x32_bf16 v[28:31], v[134:137], v[166:169], v[28:31]
	v_mfma_f32_16x16x32_bf16 v[84:87], v[122:125], v[186:189], v[84:87]
	v_mfma_f32_16x16x32_bf16 v[20:23], v[134:137], v[186:189], v[20:23]
	v_mfma_f32_16x16x32_bf16 v[76:79], v[122:125], v[204:207], v[76:79]
	v_mfma_f32_16x16x32_bf16 v[12:15], v[134:137], v[204:207], v[12:15]
	v_mfma_f32_16x16x32_bf16 v[72:75], v[122:125], v[212:215], v[72:75]
	v_mfma_f32_16x16x32_bf16 v[4:7], v[134:137], v[212:215], v[4:7]
	s_setprio 0
	s_setprio 1
	v_mfma_f32_16x16x32_bf16 v[88:91], v[138:141], v[162:165], v[88:91]
	v_mfma_f32_16x16x32_bf16 v[24:27], v[146:149], v[162:165], v[24:27]
	v_mfma_f32_16x16x32_bf16 v[80:83], v[138:141], v[170:173], v[80:83]
	v_mfma_f32_16x16x32_bf16 v[16:19], v[146:149], v[170:173], v[16:19]
	v_mfma_f32_16x16x32_bf16 v[68:71], v[138:141], v[200:203], v[68:71]
	v_mfma_f32_16x16x32_bf16 v[8:11], v[146:149], v[200:203], v[8:11]
	v_mfma_f32_16x16x32_bf16 v[64:67], v[138:141], v[208:211], v[64:67]
	v_mfma_f32_16x16x32_bf16 v[0:3], v[146:149], v[208:211], v[0:3]
	v_mfma_f32_16x16x32_bf16 v[88:91], v[142:145], v[166:169], v[88:91]
	v_mfma_f32_16x16x32_bf16 v[24:27], v[150:153], v[166:169], v[24:27]
	v_mfma_f32_16x16x32_bf16 v[80:83], v[142:145], v[186:189], v[80:83]
	v_mfma_f32_16x16x32_bf16 v[16:19], v[150:153], v[186:189], v[16:19]
	v_mfma_f32_16x16x32_bf16 v[68:71], v[142:145], v[204:207], v[68:71]
	v_mfma_f32_16x16x32_bf16 v[8:11], v[150:153], v[204:207], v[8:11]
	v_mfma_f32_16x16x32_bf16 v[64:67], v[142:145], v[212:215], v[64:67]
	v_mfma_f32_16x16x32_bf16 v[0:3], v[150:153], v[212:215], v[0:3]
	s_setprio 0
	s_barrier
; #define PG8_STAGE(bufoff, gbase, voff) do { const __amdgpu_buffer_rsrc_t _rs = __builtin_amdgcn_make_buffer_rsrc((void*)(gbase), 0, 0x7fffffff, 0x00020000); _Pragma("unroll") for (int _i = 0; _i < 2; ++_i) \
;         __builtin_amdgcn_raw_ptr_buffer_load_lds(_rs, (LAS unsigned*)(lds + (bufoff) + ldsw + _i * 8192), 16, (int)(voff)[_i], 0, 0, 0); } while (0)
; #define PG8_WAIT_V(n) asm volatile("s_waitcnt vmcnt(" #n ")" ::: "memory")
; #define PG8_WAIT_L(n) asm volatile("s_waitcnt lgkmcnt(" #n ")" ::: "memory")
; #define PG8_BAR __builtin_amdgcn_s_barrier()
; #define PG8_SCHED __builtin_amdgcn_sched_barrier(0)
; template <class Epi, class Sched, bool F8 = false>
; __device__ __forceinline__ void gemm_phase(LAS unsigned char* lds, const int lda, const int ldb, const Sched& S, const Epi& E) {
;     ...
;             PG8_LDB(B0, 1, 0); PG8_LDB(B1, 1, 1); PG8_SCHED; PG8_LDA(At, 1, 0); PG8_STAGE(PG8_SA(0, 1), a2 + hstepA, voffA);
;             PG8_WAIT_V(8); PG8_WAIT_L(0); PG8_BAR; PG8_MMA(0, 0, At, B0); PG8_MMA(0, 1, At, B1); PG8_BAR; PG8_SCHED;
;             PG8_LDA(At, 1, 1); PG8_STAGE(PG8_SB(1, 0), b3, voffB); PG8_STAGE(PG8_SB(1, 1), b3 + hstepB, voffB); PG8_STAGE(PG8_SA(1, 0), a3, voffA);
;             PG8_WAIT_V(8); PG8_WAIT_L(0); PG8_BAR; PG8_MMA(1, 0, At, B0); PG8_MMA(1, 1, At, B1); PG8_BAR; PG8_SCHED;
	ds_read_b128 v[118:121], v197
	ds_read_b128 v[122:125], v197 offset:1024
	ds_read_b128 v[130:133], v197 offset:2048
	ds_read_b128 v[134:137], v197 offset:3072
	ds_read_b128 v[138:141], v198
	ds_read_b128 v[142:145], v198 offset:1024
	ds_read_b128 v[146:149], v198 offset:2048
	ds_read_b128 v[150:153], v198 offset:3072
	s_add_u32 s12, s20, 0x100000
	s_addc_u32 s7, s7, 0
	s_and_b32 s13, s7, 0xffff
	s_mov_b32 m0, s73
	ds_read_b128 v[162:165], v196 offset:32768
	ds_read_b128 v[166:169], v196 offset:33792
	ds_read_b128 v[170:173], v196 offset:34816
	ds_read_b128 v[186:189], v196 offset:35840
	ds_read_b128 v[200:203], v196 offset:36864
	ds_read_b128 v[204:207], v196 offset:37888
	ds_read_b128 v[208:211], v196 offset:38912
	ds_read_b128 v[212:215], v196 offset:39936
	buffer_load_dwordx4 v175, s[12:15], 0 offen lds
	s_mov_b32 m0, s74
	s_nop 0
	buffer_load_dwordx4 v179, s[12:15], 0 offen lds
	s_waitcnt vmcnt(8)
	s_waitcnt lgkmcnt(0)
	s_barrier
	s_setprio 1
	v_mfma_f32_16x16x32_bf16 v[158:161], v[118:121], v[162:165], v[158:161]
	v_mfma_f32_16x16x32_bf16 v[60:63], v[130:133], v[162:165], v[60:63]
	v_mfma_f32_16x16x32_bf16 v[154:157], v[118:121], v[170:173], v[154:157]
	v_mfma_f32_16x16x32_bf16 v[52:55], v[130:133], v[170:173], v[52:55]
	v_mfma_f32_16x16x32_bf16 v[112:115], v[118:121], v[200:203], v[114:117]
	v_mfma_f32_16x16x32_bf16 v[44:47], v[130:133], v[200:203], v[44:47]
	v_mfma_f32_16x16x32_bf16 v[108:111], v[118:121], v[208:211], v[108:111]
	v_mfma_f32_16x16x32_bf16 v[36:39], v[130:133], v[208:211], v[36:39]
	v_mfma_f32_16x16x32_bf16 v[158:161], v[122:125], v[166:169], v[158:161]
	v_mfma_f32_16x16x32_bf16 v[60:63], v[134:137], v[166:169], v[60:63]
	v_mfma_f32_16x16x32_bf16 v[154:157], v[122:125], v[186:189], v[154:157]
	v_mfma_f32_16x16x32_bf16 v[52:55], v[134:137], v[186:189], v[52:55]
	v_mfma_f32_16x16x32_bf16 v[114:117], v[122:125], v[204:207], v[112:115]
	v_mfma_f32_16x16x32_bf16 v[44:47], v[134:137], v[204:207], v[44:47]
	v_mfma_f32_16x16x32_bf16 v[110:113], v[122:125], v[212:215], v[108:111]
	v_mfma_f32_16x16x32_bf16 v[36:39], v[134:137], v[212:215], v[36:39]
	s_setprio 0
	s_setprio 1
	v_mfma_f32_16x16x32_bf16 v[104:107], v[138:141], v[162:165], v[104:107]
	v_mfma_f32_16x16x32_bf16 v[56:59], v[146:149], v[162:165], v[56:59]
	v_mfma_f32_16x16x32_bf16 v[126:129], v[138:141], v[170:173], v[126:129]
	v_mfma_f32_16x16x32_bf16 v[48:51], v[146:149], v[170:173], v[48:51]
	v_mfma_f32_16x16x32_bf16 v[100:103], v[138:141], v[200:203], v[100:103]
	v_mfma_f32_16x16x32_bf16 v[40:43], v[146:149], v[200:203], v[40:43]
	v_mfma_f32_16x16x32_bf16 v[96:99], v[138:141], v[208:211], v[96:99]
	v_mfma_f32_16x16x32_bf16 v[32:35], v[146:149], v[208:211], v[32:35]
	v_mfma_f32_16x16x32_bf16 v[104:107], v[142:145], v[166:169], v[104:107]
	v_mfma_f32_16x16x32_bf16 v[56:59], v[150:153], v[166:169], v[56:59]
	v_mfma_f32_16x16x32_bf16 v[126:129], v[142:145], v[186:189], v[126:129]
	v_mfma_f32_16x16x32_bf16 v[48:51], v[150:153], v[186:189], v[48:51]
	v_mfma_f32_16x16x32_bf16 v[100:103], v[142:145], v[204:207], v[100:103]
	v_mfma_f32_16x16x32_bf16 v[40:43], v[150:153], v[204:207], v[40:43]
	v_mfma_f32_16x16x32_bf16 v[96:99], v[142:145], v[212:215], v[96:99]
	v_mfma_f32_16x16x32_bf16 v[32:35], v[150:153], v[212:215], v[32:35]
	s_setprio 0
	s_barrier
	s_add_u32 s12, s16, 0x8000
	s_addc_u32 s7, s6, 0
	s_mov_b32 m0, s78
	s_and_b32 s13, s7, 0xffff
	ds_read_b128 v[162:165], v196 offset:49152
	ds_read_b128 v[166:169], v196 offset:50176
	ds_read_b128 v[170:173], v196 offset:51200
	ds_read_b128 v[186:189], v196 offset:52224
	ds_read_b128 v[200:203], v196 offset:53248
	ds_read_b128 v[204:207], v196 offset:54272
	ds_read_b128 v[208:211], v196 offset:55296
	ds_read_b128 v[212:215], v196 offset:56320
	buffer_load_dwordx4 v177, s[12:15], 0 offen lds
	s_mov_b32 m0, s79
	s_mov_b32 s7, s15
	buffer_load_dwordx4 v193, s[12:15], 0 offen lds
	s_add_u32 s12, s16, 0xc000
	s_addc_u32 s6, s6, 0
	s_and_b32 s13, s6, 0xffff
	s_mov_b32 m0, s82
	s_and_b32 s5, s5, 0xffff
	buffer_load_dwordx4 v177, s[12:15], 0 offen lds
	s_mov_b32 m0, s83
	s_mov_b32 s6, s14
	buffer_load_dwordx4 v193, s[12:15], 0 offen lds
	s_mov_b32 m0, s80
	s_nop 0
	buffer_load_dwordx4 v175, s[4:7], 0 offen lds
	s_mov_b32 m0, s81
	s_nop 0
	buffer_load_dwordx4 v179, s[4:7], 0 offen lds
	s_waitcnt vmcnt(8)
	s_waitcnt lgkmcnt(0)
	s_barrier
	s_setprio 1
	v_mfma_f32_16x16x32_bf16 v[92:95], v[118:121], v[162:165], v[92:95]
	v_mfma_f32_16x16x32_bf16 v[28:31], v[130:133], v[162:165], v[28:31]
	v_mfma_f32_16x16x32_bf16 v[84:87], v[118:121], v[170:173], v[84:87]
	v_mfma_f32_16x16x32_bf16 v[20:23], v[130:133], v[170:173], v[20:23]
	v_mfma_f32_16x16x32_bf16 v[76:79], v[118:121], v[200:203], v[76:79]
	v_mfma_f32_16x16x32_bf16 v[12:15], v[130:133], v[200:203], v[12:15]
	v_mfma_f32_16x16x32_bf16 v[72:75], v[118:121], v[208:211], v[72:75]
	v_mfma_f32_16x16x32_bf16 v[4:7], v[130:133], v[208:211], v[4:7]
	v_mfma_f32_16x16x32_bf16 v[92:95], v[122:125], v[166:169], v[92:95]
	v_mfma_f32_16x16x32_bf16 v[28:31], v[134:137], v[166:169], v[28:31]
	v_mfma_f32_16x16x32_bf16 v[84:87], v[122:125], v[186:189], v[84:87]
	v_mfma_f32_16x16x32_bf16 v[20:23], v[134:137], v[186:189], v[20:23]
	v_mfma_f32_16x16x32_bf16 v[76:79], v[122:125], v[204:207], v[76:79]
	v_mfma_f32_16x16x32_bf16 v[12:15], v[134:137], v[204:207], v[12:15]
	v_mfma_f32_16x16x32_bf16 v[72:75], v[122:125], v[212:215], v[72:75]
	v_mfma_f32_16x16x32_bf16 v[4:7], v[134:137], v[212:215], v[4:7]
	s_setprio 0
	s_setprio 1
	v_mfma_f32_16x16x32_bf16 v[88:91], v[138:141], v[162:165], v[88:91]
	v_mfma_f32_16x16x32_bf16 v[24:27], v[146:149], v[162:165], v[24:27]
	v_mfma_f32_16x16x32_bf16 v[80:83], v[138:141], v[170:173], v[80:83]
	v_mfma_f32_16x16x32_bf16 v[16:19], v[146:149], v[170:173], v[16:19]
	v_mfma_f32_16x16x32_bf16 v[68:71], v[138:141], v[200:203], v[68:71]
	v_mfma_f32_16x16x32_bf16 v[8:11], v[146:149], v[200:203], v[8:11]
	v_mfma_f32_16x16x32_bf16 v[64:67], v[138:141], v[208:211], v[64:67]
	v_mfma_f32_16x16x32_bf16 v[0:3], v[146:149], v[208:211], v[0:3]
	v_mfma_f32_16x16x32_bf16 v[88:91], v[142:145], v[166:169], v[88:91]
	v_mfma_f32_16x16x32_bf16 v[24:27], v[150:153], v[166:169], v[24:27]
	v_mfma_f32_16x16x32_bf16 v[80:83], v[142:145], v[186:189], v[80:83]
	v_mfma_f32_16x16x32_bf16 v[16:19], v[150:153], v[186:189], v[16:19]
	v_mfma_f32_16x16x32_bf16 v[68:71], v[142:145], v[204:207], v[68:71]
	v_mfma_f32_16x16x32_bf16 v[8:11], v[150:153], v[204:207], v[8:11]
	v_mfma_f32_16x16x32_bf16 v[64:67], v[142:145], v[212:215], v[64:67]
	v_mfma_f32_16x16x32_bf16 v[0:3], v[150:153], v[212:215], v[0:3]
	s_setprio 0
	s_barrier
	s_add_i32 s45, s45, 2
	s_add_u32 s8, s8, 0x10000
	s_addc_u32 s9, s9, 0
	s_add_u32 s33, s33, 0x100
	s_addc_u32 s43, s43, 0
	s_cmp_gt_u32 s45, 61
	s_cbranch_scc0 .LBB0_778
	s_and_b64 vcc, exec, s[40:41]
	s_cbranch_vccz .LBB0_781
	s_barrier

; #define PG8_STAGE(bufoff, gbase, voff) do { const __amdgpu_buffer_rsrc_t _rs = __builtin_amdgcn_make_buffer_rsrc((void*)(gbase), 0, 0x7fffffff, 0x00020000); _Pragma("unroll") for (int _i = 0; _i < 2; ++_i) \
;         __builtin_amdgcn_raw_ptr_buffer_load_lds(_rs, (LAS unsigned*)(lds + (bufoff) + ldsw + _i * 8192), 16, (int)(voff)[_i], 0, 0, 0); } while (0)
; #define PG8_WAIT_V(n) asm volatile("s_waitcnt vmcnt(" #n ")" ::: "memory")
; #define PG8_WAIT_L(n) asm volatile("s_waitcnt lgkmcnt(" #n ")" ::: "memory")
; #define PG8_BAR __builtin_amdgcn_s_barrier()
; #define PG8_SCHED __builtin_amdgcn_sched_barrier(0)
; template <class Epi, class Sched, bool F8 = false>
; __device__ __forceinline__ void gemm_phase(LAS unsigned char* lds, const int lda, const int ldb, const Sched& S, const Epi& E) {
;     ...
;             const bool last = (t == nt - 2);
;             const char* a1 = cA + (size_t)(t + 1) * kstep;
;             const char* a2 = last ? nA : cA + (size_t)(t + 2) * kstep; const char* b2 = last ? nB : cB + (size_t)(t + 2) * kstepB;
;             const char* a3 = a2 + kstep; const char* b3 = b2 + kstepB;
;     ...
;             PG8_LDB(B0, 0, 0); PG8_LDB(B1, 0, 1); PG8_SCHED; PG8_LDA(At, 0, 0); PG8_STAGE(PG8_SA(1, 1), a1 + hstepA, voffA);
;             PG8_WAIT_V(8); PG8_WAIT_L(0); PG8_BAR; PG8_MMA(0, 0, At, B0); PG8_MMA(0, 1, At, B1); PG8_BAR; PG8_SCHED;
;             PG8_LDA(At, 0, 1); PG8_STAGE(PG8_SB(0, 0), b2, voffB); PG8_STAGE(PG8_SB(0, 1), b2 + hstepB, voffB); PG8_STAGE(PG8_SA(0, 0), a2, voffA);
;             PG8_WAIT_V(8); PG8_WAIT_L(0); PG8_BAR; PG8_MMA(1, 0, At, B0); PG8_MMA(1, 1, At, B1); PG8_BAR; PG8_SCHED;
.LBB0_935:
	ds_read_b128 v[136:139], v142
	ds_read_b128 v[148:151], v142 offset:1024
	ds_read_b128 v[152:155], v142 offset:2048
	ds_read_b128 v[156:159], v142 offset:3072
	ds_read_b128 v[160:163], v143
	ds_read_b128 v[164:167], v143 offset:1024
	ds_read_b128 v[168:171], v143 offset:2048
	ds_read_b128 v[180:183], v143 offset:3072
	s_add_u32 s4, s91, 0xffd50080
	s_addc_u32 s5, s92, -1
	s_cmpk_eq_i32 s64, 0xa8
	s_cselect_b32 s20, s44, s4
	s_cselect_b32 s15, s45, s5
	s_cselect_b32 s14, s47, s90
	s_cselect_b32 s16, s46, s89
	s_add_u32 s12, s20, 0x80
	s_addc_u32 s13, s15, 0
	s_and_b32 s5, s92, 0xffff
	s_mov_b32 s4, s91
	s_mov_b32 m0, s79
	ds_read_b128 v[184:187], v144
	ds_read_b128 v[188:191], v144 offset:1024
	ds_read_b128 v[194:197], v144 offset:2048
	ds_read_b128 v[198:201], v144 offset:3072
	ds_read_b128 v[202:205], v144 offset:4096
	ds_read_b128 v[206:209], v144 offset:5120
	ds_read_b128 v[210:213], v144 offset:6144
	ds_read_b128 v[214:217], v144 offset:7168
	buffer_load_dwordx4 v128, s[4:7], 0 offen lds
	s_mov_b32 m0, s80
	s_nop 0
	buffer_load_dwordx4 v130, s[4:7], 0 offen lds
	s_waitcnt vmcnt(8)
	s_waitcnt lgkmcnt(0)
	s_barrier
	s_setprio 1
	v_mfma_f32_16x16x32_bf16 v[124:127], v[136:139], v[184:187], v[124:127]
	v_mfma_f32_16x16x32_bf16 v[120:123], v[152:155], v[184:187], v[120:123]
	v_mfma_f32_16x16x32_bf16 v[108:111], v[136:139], v[194:197], v[108:111]
	v_mfma_f32_16x16x32_bf16 v[104:107], v[152:155], v[194:197], v[104:107]
	v_mfma_f32_16x16x32_bf16 v[92:95], v[136:139], v[202:205], v[92:95]
	v_mfma_f32_16x16x32_bf16 v[88:91], v[152:155], v[202:205], v[88:91]
	v_mfma_f32_16x16x32_bf16 v[76:79], v[136:139], v[210:213], v[76:79]
	v_mfma_f32_16x16x32_bf16 v[72:75], v[152:155], v[210:213], v[72:75]
	v_mfma_f32_16x16x32_bf16 v[124:127], v[148:151], v[188:191], v[124:127]
	v_mfma_f32_16x16x32_bf16 v[120:123], v[156:159], v[188:191], v[120:123]
	v_mfma_f32_16x16x32_bf16 v[108:111], v[148:151], v[198:201], v[108:111]
	v_mfma_f32_16x16x32_bf16 v[104:107], v[156:159], v[198:201], v[104:107]
	v_mfma_f32_16x16x32_bf16 v[92:95], v[148:151], v[206:209], v[92:95]
	v_mfma_f32_16x16x32_bf16 v[88:91], v[156:159], v[206:209], v[88:91]
	v_mfma_f32_16x16x32_bf16 v[76:79], v[148:151], v[214:217], v[76:79]
	v_mfma_f32_16x16x32_bf16 v[72:75], v[156:159], v[214:217], v[72:75]
	s_setprio 0
	s_setprio 1
	v_mfma_f32_16x16x32_bf16 v[116:119], v[160:163], v[184:187], v[116:119]
	v_mfma_f32_16x16x32_bf16 v[112:115], v[168:171], v[184:187], v[112:115]
	v_mfma_f32_16x16x32_bf16 v[100:103], v[160:163], v[194:197], v[100:103]
	v_mfma_f32_16x16x32_bf16 v[96:99], v[168:171], v[194:197], v[96:99]
	v_mfma_f32_16x16x32_bf16 v[84:87], v[160:163], v[202:205], v[84:87]
	v_mfma_f32_16x16x32_bf16 v[80:83], v[168:171], v[202:205], v[80:83]
	v_mfma_f32_16x16x32_bf16 v[68:71], v[160:163], v[210:213], v[68:71]
	v_mfma_f32_16x16x32_bf16 v[64:67], v[168:171], v[210:213], v[64:67]
	v_mfma_f32_16x16x32_bf16 v[116:119], v[164:167], v[188:191], v[116:119]
	v_mfma_f32_16x16x32_bf16 v[112:115], v[180:183], v[188:191], v[112:115]
	v_mfma_f32_16x16x32_bf16 v[100:103], v[164:167], v[198:201], v[100:103]
	v_mfma_f32_16x16x32_bf16 v[96:99], v[180:183], v[198:201], v[96:99]
	v_mfma_f32_16x16x32_bf16 v[84:87], v[164:167], v[206:209], v[84:87]
	v_mfma_f32_16x16x32_bf16 v[80:83], v[180:183], v[206:209], v[80:83]
	v_mfma_f32_16x16x32_bf16 v[68:71], v[164:167], v[214:217], v[68:71]
	v_mfma_f32_16x16x32_bf16 v[64:67], v[180:183], v[214:217], v[64:67]
	s_setprio 0
	s_barrier
	s_and_b32 s17, s14, 0xffff
	s_mov_b32 m0, s49
	s_mov_b32 s18, s6
	s_mov_b32 s19, s7
	s_add_u32 s4, s16, 0x4000
	ds_read_b128 v[184:187], v144 offset:16384
	ds_read_b128 v[188:191], v144 offset:17408
	ds_read_b128 v[194:197], v144 offset:18432
	ds_read_b128 v[198:201], v144 offset:19456
	ds_read_b128 v[202:205], v144 offset:20480
	ds_read_b128 v[206:209], v144 offset:21504
	ds_read_b128 v[210:213], v144 offset:22528
	ds_read_b128 v[214:217], v144 offset:23552
	buffer_load_dwordx4 v129, s[16:19], 0 offen lds
	s_mov_b32 m0, s50
	s_addc_u32 s5, s14, 0
	buffer_load_dwordx4 v131, s[16:19], 0 offen lds
	s_and_b32 s5, s5, 0xffff
	s_mov_b32 m0, s51
	s_and_b32 s21, s15, 0xffff
	buffer_load_dwordx4 v129, s[4:7], 0 offen lds
	s_mov_b32 m0, s52
	s_mov_b32 s22, s6
	buffer_load_dwordx4 v131, s[4:7], 0 offen lds
	s_mov_b32 s23, s7
	s_mov_b32 m0, s48
	s_nop 0
	buffer_load_dwordx4 v128, s[20:23], 0 offen lds
	s_mov_b32 m0, s53
	s_nop 0
	buffer_load_dwordx4 v130, s[20:23], 0 offen lds
	s_waitcnt vmcnt(8)
	s_waitcnt lgkmcnt(0)
	s_barrier
	s_setprio 1
	v_mfma_f32_16x16x32_bf16 v[60:63], v[136:139], v[184:187], v[60:63]
	v_mfma_f32_16x16x32_bf16 v[56:59], v[152:155], v[184:187], v[56:59]
	v_mfma_f32_16x16x32_bf16 v[44:47], v[136:139], v[194:197], v[44:47]
	v_mfma_f32_16x16x32_bf16 v[40:43], v[152:155], v[194:197], v[40:43]
	v_mfma_f32_16x16x32_bf16 v[28:31], v[136:139], v[202:205], v[28:31]
	v_mfma_f32_16x16x32_bf16 v[24:27], v[152:155], v[202:205], v[24:27]
	v_mfma_f32_16x16x32_bf16 v[12:15], v[136:139], v[210:213], v[12:15]
	v_mfma_f32_16x16x32_bf16 v[8:11], v[152:155], v[210:213], v[8:11]
	v_mfma_f32_16x16x32_bf16 v[60:63], v[148:151], v[188:191], v[60:63]
	v_mfma_f32_16x16x32_bf16 v[56:59], v[156:159], v[188:191], v[56:59]
	v_mfma_f32_16x16x32_bf16 v[44:47], v[148:151], v[198:201], v[44:47]
	v_mfma_f32_16x16x32_bf16 v[40:43], v[156:159], v[198:201], v[40:43]
	v_mfma_f32_16x16x32_bf16 v[28:31], v[148:151], v[206:209], v[28:31]
	v_mfma_f32_16x16x32_bf16 v[24:27], v[156:159], v[206:209], v[24:27]
	v_mfma_f32_16x16x32_bf16 v[12:15], v[148:151], v[214:217], v[12:15]
	v_mfma_f32_16x16x32_bf16 v[8:11], v[156:159], v[214:217], v[8:11]
	s_setprio 0
	s_setprio 1
	v_mfma_f32_16x16x32_bf16 v[52:55], v[160:163], v[184:187], v[52:55]
	v_mfma_f32_16x16x32_bf16 v[48:51], v[168:171], v[184:187], v[48:51]
	v_mfma_f32_16x16x32_bf16 v[36:39], v[160:163], v[194:197], v[36:39]
	v_mfma_f32_16x16x32_bf16 v[32:35], v[168:171], v[194:197], v[32:35]
	v_mfma_f32_16x16x32_bf16 v[20:23], v[160:163], v[202:205], v[20:23]
	v_mfma_f32_16x16x32_bf16 v[16:19], v[168:171], v[202:205], v[16:19]
	v_mfma_f32_16x16x32_bf16 v[4:7], v[160:163], v[210:213], v[4:7]
	v_mfma_f32_16x16x32_bf16 v[0:3], v[168:171], v[210:213], v[0:3]
	v_mfma_f32_16x16x32_bf16 v[52:55], v[164:167], v[188:191], v[52:55]
	v_mfma_f32_16x16x32_bf16 v[48:51], v[180:183], v[188:191], v[48:51]
	v_mfma_f32_16x16x32_bf16 v[36:39], v[164:167], v[198:201], v[36:39]
	v_mfma_f32_16x16x32_bf16 v[32:35], v[180:183], v[198:201], v[32:35]
	v_mfma_f32_16x16x32_bf16 v[20:23], v[164:167], v[206:209], v[20:23]
	v_mfma_f32_16x16x32_bf16 v[16:19], v[180:183], v[206:209], v[16:19]
	v_mfma_f32_16x16x32_bf16 v[4:7], v[164:167], v[214:217], v[4:7]
	v_mfma_f32_16x16x32_bf16 v[0:3], v[180:183], v[214:217], v[0:3]
	s_setprio 0
	s_barrier
; #define PG8_STAGE(bufoff, gbase, voff) do { const __amdgpu_buffer_rsrc_t _rs = __builtin_amdgcn_make_buffer_rsrc((void*)(gbase), 0, 0x7fffffff, 0x00020000); _Pragma("unroll") for (int _i = 0; _i < 2; ++_i) \
;         __builtin_amdgcn_raw_ptr_buffer_load_lds(_rs, (LAS unsigned*)(lds + (bufoff) + ldsw + _i * 8192), 16, (int)(voff)[_i], 0, 0, 0); } while (0)
; #define PG8_WAIT_V(n) asm volatile("s_waitcnt vmcnt(" #n ")" ::: "memory")
; #define PG8_WAIT_L(n) asm volatile("s_waitcnt lgkmcnt(" #n ")" ::: "memory")
; #define PG8_BAR __builtin_amdgcn_s_barrier()
; #define PG8_SCHED __builtin_amdgcn_sched_barrier(0)
; template <class Epi, class Sched, bool F8 = false>
; __device__ __forceinline__ void gemm_phase(LAS unsigned char* lds, const int lda, const int ldb, const Sched& S, const Epi& E) {
;     ...
;             PG8_LDB(B0, 1, 0); PG8_LDB(B1, 1, 1); PG8_SCHED; PG8_LDA(At, 1, 0); PG8_STAGE(PG8_SA(0, 1), a2 + hstepA, voffA);
;             PG8_WAIT_V(8); PG8_WAIT_L(0); PG8_BAR; PG8_MMA(0, 0, At, B0); PG8_MMA(0, 1, At, B1); PG8_BAR; PG8_SCHED;
;             PG8_LDA(At, 1, 1); PG8_STAGE(PG8_SB(1, 0), b3, voffB); PG8_STAGE(PG8_SB(1, 1), b3 + hstepB, voffB); PG8_STAGE(PG8_SA(1, 0), a3, voffA);
;             PG8_WAIT_V(8); PG8_WAIT_L(0); PG8_BAR; PG8_MMA(1, 0, At, B0); PG8_MMA(1, 1, At, B1); PG8_BAR; PG8_SCHED;
	ds_read_b128 v[136:139], v145
	ds_read_b128 v[148:151], v145 offset:1024
	ds_read_b128 v[152:155], v145 offset:2048
	ds_read_b128 v[156:159], v145 offset:3072
	ds_read_b128 v[160:163], v146
	ds_read_b128 v[164:167], v146 offset:1024
	ds_read_b128 v[168:171], v146 offset:2048
	ds_read_b128 v[180:183], v146 offset:3072
	s_add_u32 s4, s20, 0x2b0000
	s_addc_u32 s5, s15, 0
	s_and_b32 s5, s5, 0xffff
	s_mov_b32 m0, s61
	ds_read_b128 v[184:187], v144 offset:32768
	ds_read_b128 v[188:191], v144 offset:33792
	ds_read_b128 v[194:197], v144 offset:34816
	ds_read_b128 v[198:201], v144 offset:35840
	ds_read_b128 v[202:205], v144 offset:36864
	ds_read_b128 v[206:209], v144 offset:37888
	ds_read_b128 v[210:213], v144 offset:38912
	ds_read_b128 v[214:217], v144 offset:39936
	buffer_load_dwordx4 v128, s[4:7], 0 offen lds
	s_mov_b32 m0, s66
	s_nop 0
	buffer_load_dwordx4 v130, s[4:7], 0 offen lds
	s_waitcnt vmcnt(8)
	s_waitcnt lgkmcnt(0)
	s_barrier
	s_setprio 1
	v_mfma_f32_16x16x32_bf16 v[124:127], v[136:139], v[184:187], v[124:127]
	v_mfma_f32_16x16x32_bf16 v[120:123], v[152:155], v[184:187], v[120:123]
	v_mfma_f32_16x16x32_bf16 v[108:111], v[136:139], v[194:197], v[108:111]
	v_mfma_f32_16x16x32_bf16 v[104:107], v[152:155], v[194:197], v[104:107]
	v_mfma_f32_16x16x32_bf16 v[92:95], v[136:139], v[202:205], v[92:95]
	v_mfma_f32_16x16x32_bf16 v[88:91], v[152:155], v[202:205], v[88:91]
	v_mfma_f32_16x16x32_bf16 v[76:79], v[136:139], v[210:213], v[76:79]
	v_mfma_f32_16x16x32_bf16 v[72:75], v[152:155], v[210:213], v[72:75]
	v_mfma_f32_16x16x32_bf16 v[124:127], v[148:151], v[188:191], v[124:127]
	v_mfma_f32_16x16x32_bf16 v[120:123], v[156:159], v[188:191], v[120:123]
	v_mfma_f32_16x16x32_bf16 v[108:111], v[148:151], v[198:201], v[108:111]
	v_mfma_f32_16x16x32_bf16 v[104:107], v[156:159], v[198:201], v[104:107]
	v_mfma_f32_16x16x32_bf16 v[92:95], v[148:151], v[206:209], v[92:95]
	v_mfma_f32_16x16x32_bf16 v[88:91], v[156:159], v[206:209], v[88:91]
	v_mfma_f32_16x16x32_bf16 v[76:79], v[148:151], v[214:217], v[76:79]
	v_mfma_f32_16x16x32_bf16 v[72:75], v[156:159], v[214:217], v[72:75]
	s_setprio 0
	s_setprio 1
	v_mfma_f32_16x16x32_bf16 v[116:119], v[160:163], v[184:187], v[116:119]
	v_mfma_f32_16x16x32_bf16 v[112:115], v[168:171], v[184:187], v[112:115]
	v_mfma_f32_16x16x32_bf16 v[100:103], v[160:163], v[194:197], v[100:103]
	v_mfma_f32_16x16x32_bf16 v[96:99], v[168:171], v[194:197], v[96:99]
	v_mfma_f32_16x16x32_bf16 v[84:87], v[160:163], v[202:205], v[84:87]
	v_mfma_f32_16x16x32_bf16 v[80:83], v[168:171], v[202:205], v[80:83]
	v_mfma_f32_16x16x32_bf16 v[68:71], v[160:163], v[210:213], v[68:71]
	v_mfma_f32_16x16x32_bf16 v[64:67], v[168:171], v[210:213], v[64:67]
	v_mfma_f32_16x16x32_bf16 v[116:119], v[164:167], v[188:191], v[116:119]
	v_mfma_f32_16x16x32_bf16 v[112:115], v[180:183], v[188:191], v[112:115]
	v_mfma_f32_16x16x32_bf16 v[100:103], v[164:167], v[198:201], v[100:103]
	v_mfma_f32_16x16x32_bf16 v[96:99], v[180:183], v[198:201], v[96:99]
	v_mfma_f32_16x16x32_bf16 v[84:87], v[164:167], v[206:209], v[84:87]
	v_mfma_f32_16x16x32_bf16 v[80:83], v[180:183], v[206:209], v[80:83]
	v_mfma_f32_16x16x32_bf16 v[68:71], v[164:167], v[214:217], v[68:71]
	v_mfma_f32_16x16x32_bf16 v[64:67], v[180:183], v[214:217], v[64:67]
	s_setprio 0
	s_barrier
	s_add_u32 s4, s16, 0x8000
	s_addc_u32 s5, s14, 0
	s_mov_b32 m0, s73
	s_and_b32 s5, s5, 0xffff
	ds_read_b128 v[184:187], v144 offset:49152
	ds_read_b128 v[188:191], v144 offset:50176
	ds_read_b128 v[194:197], v144 offset:51200
	ds_read_b128 v[198:201], v144 offset:52224
	ds_read_b128 v[202:205], v144 offset:53248
	ds_read_b128 v[206:209], v144 offset:54272
	ds_read_b128 v[210:213], v144 offset:55296
	ds_read_b128 v[214:217], v144 offset:56320
	buffer_load_dwordx4 v129, s[4:7], 0 offen lds
	s_mov_b32 m0, s74
	s_mov_b32 s15, s7
	buffer_load_dwordx4 v131, s[4:7], 0 offen lds
	s_add_u32 s4, s16, 0xc000
	s_addc_u32 s5, s14, 0
	s_and_b32 s5, s5, 0xffff
	s_mov_b32 m0, s77
	s_and_b32 s13, s13, 0xffff
	buffer_load_dwordx4 v129, s[4:7], 0 offen lds
	s_mov_b32 m0, s78
	s_mov_b32 s14, s6
	buffer_load_dwordx4 v131, s[4:7], 0 offen lds
	s_mov_b32 m0, s75
	s_nop 0
	buffer_load_dwordx4 v128, s[12:15], 0 offen lds
	s_mov_b32 m0, s76
	s_nop 0
	buffer_load_dwordx4 v130, s[12:15], 0 offen lds
	s_waitcnt vmcnt(8)
	s_waitcnt lgkmcnt(0)
	s_barrier
	s_setprio 1
	v_mfma_f32_16x16x32_bf16 v[60:63], v[136:139], v[184:187], v[60:63]
	v_mfma_f32_16x16x32_bf16 v[56:59], v[152:155], v[184:187], v[56:59]
	v_mfma_f32_16x16x32_bf16 v[44:47], v[136:139], v[194:197], v[44:47]
	v_mfma_f32_16x16x32_bf16 v[40:43], v[152:155], v[194:197], v[40:43]
	v_mfma_f32_16x16x32_bf16 v[28:31], v[136:139], v[202:205], v[28:31]
	v_mfma_f32_16x16x32_bf16 v[24:27], v[152:155], v[202:205], v[24:27]
	v_mfma_f32_16x16x32_bf16 v[12:15], v[136:139], v[210:213], v[12:15]
	v_mfma_f32_16x16x32_bf16 v[8:11], v[152:155], v[210:213], v[8:11]
	v_mfma_f32_16x16x32_bf16 v[60:63], v[148:151], v[188:191], v[60:63]
	v_mfma_f32_16x16x32_bf16 v[56:59], v[156:159], v[188:191], v[56:59]
	v_mfma_f32_16x16x32_bf16 v[44:47], v[148:151], v[198:201], v[44:47]
	v_mfma_f32_16x16x32_bf16 v[40:43], v[156:159], v[198:201], v[40:43]
	v_mfma_f32_16x16x32_bf16 v[28:31], v[148:151], v[206:209], v[28:31]
	v_mfma_f32_16x16x32_bf16 v[24:27], v[156:159], v[206:209], v[24:27]
	v_mfma_f32_16x16x32_bf16 v[12:15], v[148:151], v[214:217], v[12:15]
	v_mfma_f32_16x16x32_bf16 v[8:11], v[156:159], v[214:217], v[8:11]
	s_setprio 0
	s_setprio 1
	v_mfma_f32_16x16x32_bf16 v[52:55], v[160:163], v[184:187], v[52:55]
	v_mfma_f32_16x16x32_bf16 v[48:51], v[168:171], v[184:187], v[48:51]
	v_mfma_f32_16x16x32_bf16 v[36:39], v[160:163], v[194:197], v[36:39]
	v_mfma_f32_16x16x32_bf16 v[32:35], v[168:171], v[194:197], v[32:35]
	v_mfma_f32_16x16x32_bf16 v[20:23], v[160:163], v[202:205], v[20:23]
	v_mfma_f32_16x16x32_bf16 v[16:19], v[168:171], v[202:205], v[16:19]
	v_mfma_f32_16x16x32_bf16 v[4:7], v[160:163], v[210:213], v[4:7]
	v_mfma_f32_16x16x32_bf16 v[0:3], v[168:171], v[210:213], v[0:3]
	v_mfma_f32_16x16x32_bf16 v[52:55], v[164:167], v[188:191], v[52:55]
	v_mfma_f32_16x16x32_bf16 v[48:51], v[180:183], v[188:191], v[48:51]
	v_mfma_f32_16x16x32_bf16 v[36:39], v[164:167], v[198:201], v[36:39]
	v_mfma_f32_16x16x32_bf16 v[32:35], v[180:183], v[198:201], v[32:35]
	v_mfma_f32_16x16x32_bf16 v[20:23], v[164:167], v[206:209], v[20:23]
	v_mfma_f32_16x16x32_bf16 v[16:19], v[180:183], v[206:209], v[16:19]
	v_mfma_f32_16x16x32_bf16 v[4:7], v[164:167], v[214:217], v[4:7]
	v_mfma_f32_16x16x32_bf16 v[0:3], v[180:183], v[214:217], v[0:3]
	s_setprio 0
	s_barrier
	s_add_i32 s64, s64, 2
	s_add_u32 s89, s89, 0x10000
	s_addc_u32 s90, s90, 0
	s_add_u32 s91, s91, 0x100
	s_addc_u32 s92, s92, 0
	s_cmpk_gt_u32 s64, 0xa9
	s_cbranch_scc0 .LBB0_935
	s_and_b64 vcc, exec, s[30:31]
	s_cbranch_vccz .LBB0_938
	s_barrier
